# P2b SSD conv + silu pass of the prompt rows hand-written: every load of an item up front, scalar block addressing, packed f32 math, whole-line transposed stores, 3 channel blocks of one 64-token block
# baseline (speedup 1.0000x reference)
; __device__ __forceinline__ void ssdconv_prompt_item(const bf16_t* PROJ, int row0, bool has_hist, int cgi, const float* w, const float* bias, bf16_t* XBC, float* state_out,
;                                                     const float* DT, const float* CS, bf16_t* XT1, bf16_t* XT2, bf16_t* BT) {
;     const int c0 = cgi * 8;
;     float wv[4][8], bv[8], h0[8], h1[8], h2[8];
; #pragma unroll
;     for (int i = 0; i < 4; ++i) { const f32x4 a = *(const f32x4*)(w + i * XBCW + c0), b = *(const f32x4*)(w + i * XBCW + c0 + 4);
;         wv[i][0] = a.x; wv[i][1] = a.y; wv[i][2] = a.z; wv[i][3] = a.w; wv[i][4] = b.x; wv[i][5] = b.y; wv[i][6] = b.z; wv[i][7] = b.w; }
;     { const f32x4 a = *(const f32x4*)(bias + c0), b = *(const f32x4*)(bias + c0 + 4);
;       bv[0] = a.x; bv[1] = a.y; bv[2] = a.z; bv[3] = a.w; bv[4] = b.x; bv[5] = b.y; bv[6] = b.z; bv[7] = b.w; }
;     u32x4 rows[8], hr[3];
; #pragma unroll
;     for (int t = 0; t < 8; ++t) rows[t] = *(const u32x4*)(PROJ + (size_t)(row0 + t) * NPROJ + CXBC + c0);
;     if (has_hist) {
; #pragma unroll
;         for (int i = 0; i < 3; ++i) hr[i] = *(const u32x4*)(PROJ + (size_t)(row0 - 3 + i) * NPROJ + CXBC + c0);
;     } else {
; #pragma unroll
;         for (int i = 0; i < 3; ++i) hr[i] = (u32x4){0u, 0u, 0u, 0u};
;     }
;     const bool isx = cgi < 256, isb = (cgi >= 256 && cgi < 320);
;     float f1[8], f2[8];
;     if (isx) { const int h = cgi >> 3; const float csl = CS[(size_t)((row0 & ~127) + 127) * NH + h];
; #pragma unroll
;         for (int t = 0; t < 8; ++t) { const float d = DT[(size_t)(row0 + t) * NH + h]; const float c = CS[(size_t)(row0 + t) * NH + h]; f1[t] = d; f2[t] = d * __expf(csl - c); } }
; __global__ void __launch_bounds__(512, 2) mk_fwd(Args args) {
;     ...
;         const int gt = vbx * 512 + tid, NGT = G * 512;
;         if (psel != 2) for (int it = gt; it < (MP / 8) * 384; it += NGT) {
;             const int cq = it & 7, tgl = (it >> 3) & 7, rest = it >> 6; const int cgi = (rest % 48) * 8 + cq, tg = (rest / 48) * 8 + tgl; const int row0 = tg * 8, t0 = row0 % SEQ, b = row0 / SEQ;
;             ssdconv_prompt_item(PROJ, row0, t0 > 0, cgi, ssd_conv_w, ssd_conv_b, XBC, (t0 == SEQ - 8) ? out + O_PSSDC + (size_t)b * 3 * XBCW : nullptr, DT, CS, XT1, XT2, BT); }
.LBB0_348:
	s_or_b64 exec, exec, s[0:1]
	v_readlane_b32 s0, v253, 2
	s_lshl_b32 s3, s94, 9
	s_mov_b32 s4, 0x60000
	v_lshl_add_u32 v168, s0, 9, v172
	v_readlane_b32 s0, v253, 6
	s_cmp_lg_u32 s0, 2
	s_cselect_b64 s[0:1], -1, 0
	v_cmp_gt_i32_e32 vcc, s4, v168
	s_and_b64 s[4:5], s[0:1], vcc
	s_waitcnt lgkmcnt(0)
	s_barrier
	s_and_saveexec_b64 s[0:1], s[4:5]
	s_cbranch_execz .LBB0_365
	s_load_dwordx4 s[12:15], s[22:23], 0x40
	v_readlane_b32 s4, v253, 2
	v_readfirstlane_b32 s9, v172
	v_and_b32_e32 v0, 7, v172
	v_bfe_u32 v1, v172, 3, 3
	s_lshr_b32 s9, s9, 6
	s_lshl_b32 s4, s4, 3
	s_add_u32 s4, s4, s9
	s_lshr_b32 s5, s4, 4
	s_and_b32 s4, s4, 15
	s_mov_b32 s6, s4
	s_lshl_b32 s9, s5, 6
	v_lshl_add_u32 v2, v1, 3, s9
	v_lshlrev_b32_e32 v12, 4, v0
	v_mov_b32_e32 v13, 0x4a00
	v_mad_u32_u24 v4, v2, v13, v12
	v_and_b32_e32 v14, 0x7ff, v2
	v_cmp_ne_u32_e64 s[44:45], 0, v14
	v_cmp_eq_u32_e32 vcc, 0x7f8, v14
	v_subrev_u32_e32 v15, 0xde00, v4
	s_nop 1
	s_mov_b64 s[46:47], vcc
	v_cndmask_b32_e64 v3, v4, v15, s[44:45]
	v_mov_b32_e32 v13, 0x1800
	v_mad_u32_u24 v5, v2, v13, v12
	v_lshlrev_b32_e32 v6, 7, v2
	v_or_b32_e32 v7, 0x7f, v2
	v_lshlrev_b32_e32 v7, 7, v7
	v_lshrrev_b32_e32 v13, 7, v2
	v_and_b32_e32 v14, 0x7f, v2
	v_lshlrev_b32_e32 v14, 1, v14
	v_lshl_add_u32 v14, v0, 11, v14
	v_lshl_add_u32 v8, v13, 19, v14
	v_lshl_add_u32 v9, v13, 17, v14
	v_lshlrev_b32_e32 v10, 5, v0
	v_lshrrev_b32_e32 v13, 11, v2
	v_mov_b32_e32 v14, 0x9000
	v_mad_u32_u24 v11, v13, v14, v10
	v_mov_b32_e32 v12, 0xbfb8aa3b
	v_mov_b32_e32 v13, 1.0
	v_mov_b32_e32 v14, 0x3fb8aa3b
	s_mov_b32 s7, 0
	s_waitcnt lgkmcnt(0)
.Lp2b_item:
	s_lshl_b32 s8, s7, 4
	s_add_u32 s8, s8, s6
	s_lshl_b32 s9, s8, 8
	s_add_u32 s26, s12, s9
	s_addc_u32 s27, s13, 0
	global_load_dwordx4 v[16:19], v10, s[26:27]
	global_load_dwordx4 v[20:23], v10, s[26:27] offset:16
	s_add_u32 s26, s26, 0x3000
	s_addc_u32 s27, s27, 0
	global_load_dwordx4 v[24:27], v10, s[26:27]
	global_load_dwordx4 v[28:31], v10, s[26:27] offset:16
	s_add_u32 s26, s26, 0x3000
	s_addc_u32 s27, s27, 0
	global_load_dwordx4 v[32:35], v10, s[26:27]
	global_load_dwordx4 v[36:39], v10, s[26:27] offset:16
	s_add_u32 s26, s26, 0x3000
	s_addc_u32 s27, s27, 0
	global_load_dwordx4 v[40:43], v10, s[26:27]
	global_load_dwordx4 v[44:47], v10, s[26:27] offset:16
	s_add_u32 s26, s14, s9
	s_addc_u32 s27, s15, 0
	global_load_dwordx4 v[48:51], v10, s[26:27]
	global_load_dwordx4 v[52:55], v10, s[26:27] offset:16
	s_lshl_b32 s10, s8, 7
	s_add_u32 s26, s18, 0x9891000
	s_addc_u32 s27, s19, 0
	s_add_u32 s26, s26, s10
	s_addc_u32 s27, s27, 0
	s_mov_b32 s28, s26
	s_mov_b32 s29, s27
	global_load_dwordx4 v[56:59], v3, s[28:29]
	s_add_u32 s28, s28, 0x4a00
	s_addc_u32 s29, s29, 0
	global_load_dwordx4 v[60:63], v3, s[28:29]
	s_add_u32 s28, s28, 0x4a00
	s_addc_u32 s29, s29, 0
	global_load_dwordx4 v[64:67], v3, s[28:29]
	global_load_dwordx4 v[68:71], v4, s[26:27]
	s_add_u32 s26, s26, 0x4a00
	s_addc_u32 s27, s27, 0
	global_load_dwordx4 v[72:75], v4, s[26:27]
	s_add_u32 s26, s26, 0x4a00
	s_addc_u32 s27, s27, 0
	global_load_dwordx4 v[76:79], v4, s[26:27]
	s_add_u32 s26, s26, 0x4a00
	s_addc_u32 s27, s27, 0
	global_load_dwordx4 v[80:83], v4, s[26:27]
	s_add_u32 s26, s26, 0x4a00
	s_addc_u32 s27, s27, 0
	global_load_dwordx4 v[84:87], v4, s[26:27]
	s_add_u32 s26, s26, 0x4a00
	s_addc_u32 s27, s27, 0
	global_load_dwordx4 v[88:91], v4, s[26:27]
	s_add_u32 s26, s26, 0x4a00
	s_addc_u32 s27, s27, 0
	global_load_dwordx4 v[92:95], v4, s[26:27]
	s_add_u32 s26, s26, 0x4a00
	s_addc_u32 s27, s27, 0
	global_load_dwordx4 v[96:99], v4, s[26:27]
	s_add_u32 s30, s18, 0x135d0000
	s_addc_u32 s31, s19, 0
	s_add_u32 s30, s30, s10
	s_addc_u32 s31, s31, 0
	s_add_u32 s38, s16, 0x4800000
	s_addc_u32 s39, s17, 0
	s_add_u32 s38, s38, s9
	s_addc_u32 s39, s39, 0
	s_cmp_lt_u32 s8, 32
	s_cbranch_scc0 .Lp2b_notx
	s_lshl_b32 s11, s8, 2
	s_add_u32 s40, s18, 0x9780000
	s_addc_u32 s41, s19, 0
	s_add_u32 s40, s40, s11
	s_addc_u32 s41, s41, 0
	s_add_u32 s42, s24, s11
	s_addc_u32 s43, s25, 0
	global_load_dword v152, v6, s[40:41] offset:0
	global_load_dword v153, v6, s[40:41] offset:128
	global_load_dword v154, v6, s[40:41] offset:256
	global_load_dword v155, v6, s[40:41] offset:384
	global_load_dword v156, v6, s[40:41] offset:512
	global_load_dword v157, v6, s[40:41] offset:640
	global_load_dword v158, v6, s[40:41] offset:768
	global_load_dword v159, v6, s[40:41] offset:896
	global_load_dword v160, v6, s[42:43] offset:0
	global_load_dword v161, v6, s[42:43] offset:128
	global_load_dword v162, v6, s[42:43] offset:256
	global_load_dword v163, v6, s[42:43] offset:384
	global_load_dword v164, v6, s[42:43] offset:512
	global_load_dword v165, v6, s[42:43] offset:640
	global_load_dword v166, v6, s[42:43] offset:768
	global_load_dword v167, v6, s[42:43] offset:896
	global_load_dword v168, v7, s[42:43]
	s_lshl_b32 s11, s8, 14
	s_add_u32 s34, s18, 0x7580000
	s_addc_u32 s35, s19, 0
	s_add_u32 s34, s34, s11
	s_addc_u32 s35, s35, 0
	s_add_u32 s36, s16, s11
	s_addc_u32 s37, s17, 0
	s_waitcnt vmcnt(0)
; __device__ __forceinline__ float siluf_(float x) { return x * __builtin_amdgcn_rcpf(1.f + __expf(-x)); }
; __device__ __forceinline__ void ssdconv_prompt_item(const bf16_t* PROJ, int row0, bool has_hist, int cgi, const float* w, const float* bias, bf16_t* XBC, float* state_out,
;                                                     const float* DT, const float* CS, bf16_t* XT1, bf16_t* XT2, bf16_t* BT) {
;     ...
;         for (int t = 0; t < 8; ++t) { const float d = DT[(size_t)(row0 + t) * NH + h]; const float c = CS[(size_t)(row0 + t) * NH + h]; f1[t] = d; f2[t] = d * __expf(csl - c); } }
;     unpack8(hr[0], h0); unpack8(hr[1], h1); unpack8(hr[2], h2);
;     float o[8][8];
; #pragma unroll
;     for (int t = 0; t < 8; ++t) {
;         float cur[8];
;         unpack8(rows[t], cur);
; #pragma unroll
;         for (int e = 0; e < 8; ++e) { float v = h0[e] * wv[0][e] + h1[e] * wv[1][e] + h2[e] * wv[2][e] + cur[e] * wv[3][e] + bv[e]; o[t][e] = siluf_(v); h0[e] = h1[e]; h1[e] = h2[e]; h2[e] = cur[e]; }
;         *(u32x4*)(XBC + (size_t)(row0 + t) * XBCW + c0) = pack8(o[t]);
	v_sub_f32_e32 v160, v168, v160
	v_sub_f32_e32 v161, v168, v161
	v_sub_f32_e32 v162, v168, v162
	v_sub_f32_e32 v163, v168, v163
	v_sub_f32_e32 v164, v168, v164
	v_sub_f32_e32 v165, v168, v165
	v_sub_f32_e32 v166, v168, v166
	v_sub_f32_e32 v167, v168, v167
	v_mul_f32_e32 v160, v14, v160
	v_mul_f32_e32 v161, v14, v161
	v_mul_f32_e32 v162, v14, v162
	v_mul_f32_e32 v163, v14, v163
	v_mul_f32_e32 v164, v14, v164
	v_mul_f32_e32 v165, v14, v165
	v_mul_f32_e32 v166, v14, v166
	v_mul_f32_e32 v167, v14, v167
	v_exp_f32_e32 v160, v160
	v_exp_f32_e32 v161, v161
	v_exp_f32_e32 v162, v162
	v_exp_f32_e32 v163, v163
	v_exp_f32_e32 v164, v164
	v_exp_f32_e32 v165, v165
	v_exp_f32_e32 v166, v166
	v_exp_f32_e32 v167, v167
	s_nop 0
	v_mul_f32_e32 v160, v152, v160
	v_mul_f32_e32 v161, v153, v161
	v_mul_f32_e32 v162, v154, v162
	v_mul_f32_e32 v163, v155, v163
	v_mul_f32_e32 v164, v156, v164
	v_mul_f32_e32 v165, v157, v165
	v_mul_f32_e32 v166, v158, v166
	v_mul_f32_e32 v167, v159, v167
	v_cndmask_b32_e64 v56, 0, v56, s[44:45]
	v_cndmask_b32_e64 v57, 0, v57, s[44:45]
	v_cndmask_b32_e64 v58, 0, v58, s[44:45]
	v_cndmask_b32_e64 v59, 0, v59, s[44:45]
	v_cndmask_b32_e64 v60, 0, v60, s[44:45]
	v_cndmask_b32_e64 v61, 0, v61, s[44:45]
	v_cndmask_b32_e64 v62, 0, v62, s[44:45]
	v_cndmask_b32_e64 v63, 0, v63, s[44:45]
	v_cndmask_b32_e64 v64, 0, v64, s[44:45]
	v_cndmask_b32_e64 v65, 0, v65, s[44:45]
	v_cndmask_b32_e64 v66, 0, v66, s[44:45]
	v_cndmask_b32_e64 v67, 0, v67, s[44:45]
	v_lshlrev_b32_e32 v100, 16, v56
	v_and_b32_e32 v101, 0xffff0000, v56
	v_lshlrev_b32_e32 v102, 16, v57
	v_and_b32_e32 v103, 0xffff0000, v57
	v_lshlrev_b32_e32 v104, 16, v58
	v_and_b32_e32 v105, 0xffff0000, v58
	v_lshlrev_b32_e32 v106, 16, v59
	v_and_b32_e32 v107, 0xffff0000, v59
	v_lshlrev_b32_e32 v108, 16, v60
	v_and_b32_e32 v109, 0xffff0000, v60
	v_lshlrev_b32_e32 v110, 16, v61
	v_and_b32_e32 v111, 0xffff0000, v61
	v_lshlrev_b32_e32 v112, 16, v62
	v_and_b32_e32 v113, 0xffff0000, v62
	v_lshlrev_b32_e32 v114, 16, v63
	v_and_b32_e32 v115, 0xffff0000, v63
	v_lshlrev_b32_e32 v116, 16, v64
	v_and_b32_e32 v117, 0xffff0000, v64
	v_lshlrev_b32_e32 v118, 16, v65
	v_and_b32_e32 v119, 0xffff0000, v65
	v_lshlrev_b32_e32 v120, 16, v66
	v_and_b32_e32 v121, 0xffff0000, v66
	v_lshlrev_b32_e32 v122, 16, v67
	v_and_b32_e32 v123, 0xffff0000, v67
	v_lshlrev_b32_e32 v124, 16, v68
	v_and_b32_e32 v125, 0xffff0000, v68
	v_lshlrev_b32_e32 v126, 16, v69
	v_and_b32_e32 v127, 0xffff0000, v69
	v_lshlrev_b32_e32 v128, 16, v70
	v_and_b32_e32 v129, 0xffff0000, v70
	v_lshlrev_b32_e32 v130, 16, v71
	v_and_b32_e32 v131, 0xffff0000, v71
	v_pk_mul_f32 v[132:133], v[100:101], v[16:17]
	v_pk_fma_f32 v[132:133], v[108:109], v[24:25], v[132:133]
	v_pk_fma_f32 v[132:133], v[116:117], v[32:33], v[132:133]
	v_pk_fma_f32 v[132:133], v[124:125], v[40:41], v[132:133]
	v_pk_add_f32 v[132:133], v[132:133], v[48:49]
	v_pk_mul_f32 v[134:135], v[102:103], v[18:19]
	v_pk_fma_f32 v[134:135], v[110:111], v[26:27], v[134:135]
	v_pk_fma_f32 v[134:135], v[118:119], v[34:35], v[134:135]
	v_pk_fma_f32 v[134:135], v[126:127], v[42:43], v[134:135]
	v_pk_add_f32 v[134:135], v[134:135], v[50:51]
	v_pk_mul_f32 v[136:137], v[104:105], v[20:21]
	v_pk_fma_f32 v[136:137], v[112:113], v[28:29], v[136:137]
	v_pk_fma_f32 v[136:137], v[120:121], v[36:37], v[136:137]
	v_pk_fma_f32 v[136:137], v[128:129], v[44:45], v[136:137]
	v_pk_add_f32 v[136:137], v[136:137], v[52:53]
	v_pk_mul_f32 v[138:139], v[106:107], v[22:23]
	v_pk_fma_f32 v[138:139], v[114:115], v[30:31], v[138:139]
	v_pk_fma_f32 v[138:139], v[122:123], v[38:39], v[138:139]
	v_pk_fma_f32 v[138:139], v[130:131], v[46:47], v[138:139]
	v_pk_add_f32 v[138:139], v[138:139], v[54:55]
	v_pk_mul_f32 v[140:141], v[132:133], v[12:13] op_sel:[0,0] op_sel_hi:[1,0]
	v_pk_mul_f32 v[142:143], v[134:135], v[12:13] op_sel:[0,0] op_sel_hi:[1,0]
	v_pk_mul_f32 v[144:145], v[136:137], v[12:13] op_sel:[0,0] op_sel_hi:[1,0]
	v_pk_mul_f32 v[146:147], v[138:139], v[12:13] op_sel:[0,0] op_sel_hi:[1,0]
	v_exp_f32_e32 v140, v140
	v_exp_f32_e32 v141, v141
	v_exp_f32_e32 v142, v142
	v_exp_f32_e32 v143, v143
	v_exp_f32_e32 v144, v144
	v_exp_f32_e32 v145, v145
	v_exp_f32_e32 v146, v146
	v_exp_f32_e32 v147, v147
	v_pk_add_f32 v[140:141], v[140:141], v[12:13] op_sel:[0,1] op_sel_hi:[1,1]
	v_pk_add_f32 v[142:143], v[142:143], v[12:13] op_sel:[0,1] op_sel_hi:[1,1]
	v_pk_add_f32 v[144:145], v[144:145], v[12:13] op_sel:[0,1] op_sel_hi:[1,1]
	v_pk_add_f32 v[146:147], v[146:147], v[12:13] op_sel:[0,1] op_sel_hi:[1,1]
	v_rcp_f32_e32 v140, v140
	v_rcp_f32_e32 v141, v141
	v_rcp_f32_e32 v142, v142
	v_rcp_f32_e32 v143, v143
	v_rcp_f32_e32 v144, v144
	v_rcp_f32_e32 v145, v145
	v_rcp_f32_e32 v146, v146
	v_rcp_f32_e32 v147, v147
	v_pk_mul_f32 v[140:141], v[132:133], v[140:141]
	v_pk_mul_f32 v[142:143], v[134:135], v[142:143]
	v_pk_mul_f32 v[144:145], v[136:137], v[144:145]
	v_pk_mul_f32 v[146:147], v[138:139], v[146:147]
	v_cvt_pk_bf16_f32 v148, v140, v141
	v_cvt_pk_bf16_f32 v149, v142, v143
	v_cvt_pk_bf16_f32 v150, v144, v145
	v_cvt_pk_bf16_f32 v151, v146, v147
	global_store_dwordx4 v5, v[148:151], s[30:31]
	s_add_u32 s30, s30, 0x1800
	s_addc_u32 s31, s31, 0
	v_pk_mul_f32 v[170:171], v[140:141], v[152:153] op_sel:[0,0] op_sel_hi:[1,0]
	v_pk_mul_f32 v[178:179], v[140:141], v[160:161] op_sel:[0,0] op_sel_hi:[1,0]
	v_pk_mul_f32 v[172:173], v[142:143], v[152:153] op_sel:[0,0] op_sel_hi:[1,0]
	v_pk_mul_f32 v[180:181], v[142:143], v[160:161] op_sel:[0,0] op_sel_hi:[1,0]
	v_pk_mul_f32 v[174:175], v[144:145], v[152:153] op_sel:[0,0] op_sel_hi:[1,0]
	v_pk_mul_f32 v[182:183], v[144:145], v[160:161] op_sel:[0,0] op_sel_hi:[1,0]
; __device__ __forceinline__ unsigned pk2(float lo, float hi) { unsigned r; asm("v_cvt_pk_bf16_f32 %0, %1, %2" : "=v"(r) : "v"(lo), "v"(hi)); return r; }
; __device__ __forceinline__ float siluf_(float x) { return x * __builtin_amdgcn_rcpf(1.f + __expf(-x)); }
; __device__ __forceinline__ void ssdconv_prompt_item(const bf16_t* PROJ, int row0, bool has_hist, int cgi, const float* w, const float* bias, bf16_t* XBC, float* state_out,
;                                                     const float* DT, const float* CS, bf16_t* XT1, bf16_t* XT2, bf16_t* BT) {
;     ...
;     for (int t = 0; t < 8; ++t) {
;         float cur[8];
;         unpack8(rows[t], cur);
; #pragma unroll
;         for (int e = 0; e < 8; ++e) { float v = h0[e] * wv[0][e] + h1[e] * wv[1][e] + h2[e] * wv[2][e] + cur[e] * wv[3][e] + bv[e]; o[t][e] = siluf_(v); h0[e] = h1[e]; h1[e] = h2[e]; h2[e] = cur[e]; }
;         *(u32x4*)(XBC + (size_t)(row0 + t) * XBCW + c0) = pack8(o[t]);
;     }
;     if (state_out) {
;         *(f32x4*)(state_out + 0 * XBCW + c0) = (f32x4){h0[0], h0[1], h0[2], h0[3]}; *(f32x4*)(state_out + 0 * XBCW + c0 + 4) = (f32x4){h0[4], h0[5], h0[6], h0[7]};
;         *(f32x4*)(state_out + 1 * XBCW + c0) = (f32x4){h1[0], h1[1], h1[2], h1[3]}; *(f32x4*)(state_out + 1 * XBCW + c0 + 4) = (f32x4){h1[4], h1[5], h1[6], h1[7]};
;         *(f32x4*)(state_out + 2 * XBCW + c0) = (f32x4){h2[0], h2[1], h2[2], h2[3]}; *(f32x4*)(state_out + 2 * XBCW + c0 + 4) = (f32x4){h2[4], h2[5], h2[6], h2[7]};
;     }
;     const int chunk = row0 >> 7, jb = row0 & 127;
;     if (isx) {
; #pragma unroll
;         for (int e = 0; e < 8; ++e) { u32x4 a, b2;
;             a.x = pk2(o[0][e] * f1[0], o[1][e] * f1[1]); a.y = pk2(o[2][e] * f1[2], o[3][e] * f1[3]); a.z = pk2(o[4][e] * f1[4], o[5][e] * f1[5]); a.w = pk2(o[6][e] * f1[6], o[7][e] * f1[7]);
;             b2.x = pk2(o[0][e] * f2[0], o[1][e] * f2[1]); b2.y = pk2(o[2][e] * f2[2], o[3][e] * f2[3]); b2.z = pk2(o[4][e] * f2[4], o[5][e] * f2[5]); b2.w = pk2(o[6][e] * f2[6], o[7][e] * f2[7]);
;             const size_t off = ((size_t)chunk * DM + c0 + e) * 128 + jb;
;             *(u32x4*)(XT1 + off) = a; *(u32x4*)(XT2 + off) = b2; }
	v_pk_mul_f32 v[176:177], v[146:147], v[152:153] op_sel:[0,0] op_sel_hi:[1,0]
	v_pk_mul_f32 v[184:185], v[146:147], v[160:161] op_sel:[0,0] op_sel_hi:[1,0]
	v_lshlrev_b32_e32 v100, 16, v72
	v_and_b32_e32 v101, 0xffff0000, v72
	v_lshlrev_b32_e32 v102, 16, v73
	v_and_b32_e32 v103, 0xffff0000, v73
	v_lshlrev_b32_e32 v104, 16, v74
	v_and_b32_e32 v105, 0xffff0000, v74
	v_lshlrev_b32_e32 v106, 16, v75
	v_and_b32_e32 v107, 0xffff0000, v75
	v_pk_mul_f32 v[132:133], v[108:109], v[16:17]
	v_pk_fma_f32 v[132:133], v[116:117], v[24:25], v[132:133]
	v_pk_fma_f32 v[132:133], v[124:125], v[32:33], v[132:133]
	v_pk_fma_f32 v[132:133], v[100:101], v[40:41], v[132:133]
	v_pk_add_f32 v[132:133], v[132:133], v[48:49]
	v_pk_mul_f32 v[134:135], v[110:111], v[18:19]
	v_pk_fma_f32 v[134:135], v[118:119], v[26:27], v[134:135]
	v_pk_fma_f32 v[134:135], v[126:127], v[34:35], v[134:135]
	v_pk_fma_f32 v[134:135], v[102:103], v[42:43], v[134:135]
	v_pk_add_f32 v[134:135], v[134:135], v[50:51]
	v_pk_mul_f32 v[136:137], v[112:113], v[20:21]
	v_pk_fma_f32 v[136:137], v[120:121], v[28:29], v[136:137]
	v_pk_fma_f32 v[136:137], v[128:129], v[36:37], v[136:137]
	v_pk_fma_f32 v[136:137], v[104:105], v[44:45], v[136:137]
	v_pk_add_f32 v[136:137], v[136:137], v[52:53]
	v_pk_mul_f32 v[138:139], v[114:115], v[22:23]
	v_pk_fma_f32 v[138:139], v[122:123], v[30:31], v[138:139]
	v_pk_fma_f32 v[138:139], v[130:131], v[38:39], v[138:139]
	v_pk_fma_f32 v[138:139], v[106:107], v[46:47], v[138:139]
	v_pk_add_f32 v[138:139], v[138:139], v[54:55]
	v_pk_mul_f32 v[140:141], v[132:133], v[12:13] op_sel:[0,0] op_sel_hi:[1,0]
	v_pk_mul_f32 v[142:143], v[134:135], v[12:13] op_sel:[0,0] op_sel_hi:[1,0]
	v_pk_mul_f32 v[144:145], v[136:137], v[12:13] op_sel:[0,0] op_sel_hi:[1,0]
	v_pk_mul_f32 v[146:147], v[138:139], v[12:13] op_sel:[0,0] op_sel_hi:[1,0]
	v_exp_f32_e32 v140, v140
	v_exp_f32_e32 v141, v141
	v_exp_f32_e32 v142, v142
	v_exp_f32_e32 v143, v143
	v_exp_f32_e32 v144, v144
	v_exp_f32_e32 v145, v145
	v_exp_f32_e32 v146, v146
	v_exp_f32_e32 v147, v147
	v_pk_add_f32 v[140:141], v[140:141], v[12:13] op_sel:[0,1] op_sel_hi:[1,1]
	v_pk_add_f32 v[142:143], v[142:143], v[12:13] op_sel:[0,1] op_sel_hi:[1,1]
	v_pk_add_f32 v[144:145], v[144:145], v[12:13] op_sel:[0,1] op_sel_hi:[1,1]
	v_pk_add_f32 v[146:147], v[146:147], v[12:13] op_sel:[0,1] op_sel_hi:[1,1]
	v_rcp_f32_e32 v140, v140
	v_rcp_f32_e32 v141, v141
	v_rcp_f32_e32 v142, v142
	v_rcp_f32_e32 v143, v143
	v_rcp_f32_e32 v144, v144
	v_rcp_f32_e32 v145, v145
	v_rcp_f32_e32 v146, v146
	v_rcp_f32_e32 v147, v147
	v_pk_mul_f32 v[140:141], v[132:133], v[140:141]
	v_pk_mul_f32 v[142:143], v[134:135], v[142:143]
	v_pk_mul_f32 v[144:145], v[136:137], v[144:145]
	v_pk_mul_f32 v[146:147], v[138:139], v[146:147]
	v_cvt_pk_bf16_f32 v148, v140, v141
	v_cvt_pk_bf16_f32 v149, v142, v143
	v_cvt_pk_bf16_f32 v150, v144, v145
	v_cvt_pk_bf16_f32 v151, v146, v147
	global_store_dwordx4 v5, v[148:151], s[30:31]
	s_add_u32 s30, s30, 0x1800
	s_addc_u32 s31, s31, 0
	v_pk_mul_f32 v[132:133], v[140:141], v[152:153] op_sel:[0,1] op_sel_hi:[1,1]
	v_pk_mul_f32 v[56:57], v[140:141], v[160:161] op_sel:[0,1] op_sel_hi:[1,1]
	v_pk_mul_f32 v[134:135], v[142:143], v[152:153] op_sel:[0,1] op_sel_hi:[1,1]
	v_pk_mul_f32 v[58:59], v[142:143], v[160:161] op_sel:[0,1] op_sel_hi:[1,1]
	v_pk_mul_f32 v[136:137], v[144:145], v[152:153] op_sel:[0,1] op_sel_hi:[1,1]
	v_pk_mul_f32 v[60:61], v[144:145], v[160:161] op_sel:[0,1] op_sel_hi:[1,1]
	v_pk_mul_f32 v[138:139], v[146:147], v[152:153] op_sel:[0,1] op_sel_hi:[1,1]
	v_pk_mul_f32 v[62:63], v[146:147], v[160:161] op_sel:[0,1] op_sel_hi:[1,1]
	v_cvt_pk_bf16_f32 v214, v170, v132
	v_cvt_pk_bf16_f32 v186, v178, v56
	v_cvt_pk_bf16_f32 v218, v171, v133
	v_cvt_pk_bf16_f32 v190, v179, v57
	v_cvt_pk_bf16_f32 v222, v172, v134
	v_cvt_pk_bf16_f32 v194, v180, v58
	v_cvt_pk_bf16_f32 v226, v173, v135
	v_cvt_pk_bf16_f32 v198, v181, v59
	v_cvt_pk_bf16_f32 v230, v174, v136
	v_cvt_pk_bf16_f32 v202, v182, v60
	v_cvt_pk_bf16_f32 v234, v175, v137
	v_cvt_pk_bf16_f32 v206, v183, v61
	v_cvt_pk_bf16_f32 v238, v176, v138
	v_cvt_pk_bf16_f32 v64, v184, v62
	v_cvt_pk_bf16_f32 v242, v177, v139
	v_cvt_pk_bf16_f32 v248, v185, v63
	v_lshlrev_b32_e32 v108, 16, v76
	v_and_b32_e32 v109, 0xffff0000, v76
	v_lshlrev_b32_e32 v110, 16, v77
	v_and_b32_e32 v111, 0xffff0000, v77
	v_lshlrev_b32_e32 v112, 16, v78
	v_and_b32_e32 v113, 0xffff0000, v78
	v_lshlrev_b32_e32 v114, 16, v79
	v_and_b32_e32 v115, 0xffff0000, v79
	v_pk_mul_f32 v[132:133], v[116:117], v[16:17]
	v_pk_fma_f32 v[132:133], v[124:125], v[24:25], v[132:133]
	v_pk_fma_f32 v[132:133], v[100:101], v[32:33], v[132:133]
	v_pk_fma_f32 v[132:133], v[108:109], v[40:41], v[132:133]
	v_pk_add_f32 v[132:133], v[132:133], v[48:49]
	v_pk_mul_f32 v[134:135], v[118:119], v[18:19]
	v_pk_fma_f32 v[134:135], v[126:127], v[26:27], v[134:135]
	v_pk_fma_f32 v[134:135], v[102:103], v[34:35], v[134:135]
	v_pk_fma_f32 v[134:135], v[110:111], v[42:43], v[134:135]
	v_pk_add_f32 v[134:135], v[134:135], v[50:51]
	v_pk_mul_f32 v[136:137], v[120:121], v[20:21]
	v_pk_fma_f32 v[136:137], v[128:129], v[28:29], v[136:137]
	v_pk_fma_f32 v[136:137], v[104:105], v[36:37], v[136:137]
	v_pk_fma_f32 v[136:137], v[112:113], v[44:45], v[136:137]
	v_pk_add_f32 v[136:137], v[136:137], v[52:53]
	v_pk_mul_f32 v[138:139], v[122:123], v[22:23]
	v_pk_fma_f32 v[138:139], v[130:131], v[30:31], v[138:139]
	v_pk_fma_f32 v[138:139], v[106:107], v[38:39], v[138:139]
	v_pk_fma_f32 v[138:139], v[114:115], v[46:47], v[138:139]
	v_pk_add_f32 v[138:139], v[138:139], v[54:55]
	v_pk_mul_f32 v[140:141], v[132:133], v[12:13] op_sel:[0,0] op_sel_hi:[1,0]
; __device__ __forceinline__ unsigned pk2(float lo, float hi) { unsigned r; asm("v_cvt_pk_bf16_f32 %0, %1, %2" : "=v"(r) : "v"(lo), "v"(hi)); return r; }
; __device__ __forceinline__ float siluf_(float x) { return x * __builtin_amdgcn_rcpf(1.f + __expf(-x)); }
; __device__ __forceinline__ void ssdconv_prompt_item(const bf16_t* PROJ, int row0, bool has_hist, int cgi, const float* w, const float* bias, bf16_t* XBC, float* state_out,
;                                                     const float* DT, const float* CS, bf16_t* XT1, bf16_t* XT2, bf16_t* BT) {
;     ...
;     for (int t = 0; t < 8; ++t) {
;         float cur[8];
;         unpack8(rows[t], cur);
; #pragma unroll
;         for (int e = 0; e < 8; ++e) { float v = h0[e] * wv[0][e] + h1[e] * wv[1][e] + h2[e] * wv[2][e] + cur[e] * wv[3][e] + bv[e]; o[t][e] = siluf_(v); h0[e] = h1[e]; h1[e] = h2[e]; h2[e] = cur[e]; }
;         *(u32x4*)(XBC + (size_t)(row0 + t) * XBCW + c0) = pack8(o[t]);
;     }
;     if (state_out) {
;         *(f32x4*)(state_out + 0 * XBCW + c0) = (f32x4){h0[0], h0[1], h0[2], h0[3]}; *(f32x4*)(state_out + 0 * XBCW + c0 + 4) = (f32x4){h0[4], h0[5], h0[6], h0[7]};
;         *(f32x4*)(state_out + 1 * XBCW + c0) = (f32x4){h1[0], h1[1], h1[2], h1[3]}; *(f32x4*)(state_out + 1 * XBCW + c0 + 4) = (f32x4){h1[4], h1[5], h1[6], h1[7]};
;         *(f32x4*)(state_out + 2 * XBCW + c0) = (f32x4){h2[0], h2[1], h2[2], h2[3]}; *(f32x4*)(state_out + 2 * XBCW + c0 + 4) = (f32x4){h2[4], h2[5], h2[6], h2[7]};
;     }
;     const int chunk = row0 >> 7, jb = row0 & 127;
;     if (isx) {
; #pragma unroll
;         for (int e = 0; e < 8; ++e) { u32x4 a, b2;
;             a.x = pk2(o[0][e] * f1[0], o[1][e] * f1[1]); a.y = pk2(o[2][e] * f1[2], o[3][e] * f1[3]); a.z = pk2(o[4][e] * f1[4], o[5][e] * f1[5]); a.w = pk2(o[6][e] * f1[6], o[7][e] * f1[7]);
;             b2.x = pk2(o[0][e] * f2[0], o[1][e] * f2[1]); b2.y = pk2(o[2][e] * f2[2], o[3][e] * f2[3]); b2.z = pk2(o[4][e] * f2[4], o[5][e] * f2[5]); b2.w = pk2(o[6][e] * f2[6], o[7][e] * f2[7]);
;             const size_t off = ((size_t)chunk * DM + c0 + e) * 128 + jb;
;             *(u32x4*)(XT1 + off) = a; *(u32x4*)(XT2 + off) = b2; }
	v_pk_mul_f32 v[142:143], v[134:135], v[12:13] op_sel:[0,0] op_sel_hi:[1,0]
	v_pk_mul_f32 v[144:145], v[136:137], v[12:13] op_sel:[0,0] op_sel_hi:[1,0]
	v_pk_mul_f32 v[146:147], v[138:139], v[12:13] op_sel:[0,0] op_sel_hi:[1,0]
	v_exp_f32_e32 v140, v140
	v_exp_f32_e32 v141, v141
	v_exp_f32_e32 v142, v142
	v_exp_f32_e32 v143, v143
	v_exp_f32_e32 v144, v144
	v_exp_f32_e32 v145, v145
	v_exp_f32_e32 v146, v146
	v_exp_f32_e32 v147, v147
	v_pk_add_f32 v[140:141], v[140:141], v[12:13] op_sel:[0,1] op_sel_hi:[1,1]
	v_pk_add_f32 v[142:143], v[142:143], v[12:13] op_sel:[0,1] op_sel_hi:[1,1]
	v_pk_add_f32 v[144:145], v[144:145], v[12:13] op_sel:[0,1] op_sel_hi:[1,1]
	v_pk_add_f32 v[146:147], v[146:147], v[12:13] op_sel:[0,1] op_sel_hi:[1,1]
	v_rcp_f32_e32 v140, v140
	v_rcp_f32_e32 v141, v141
	v_rcp_f32_e32 v142, v142
	v_rcp_f32_e32 v143, v143
	v_rcp_f32_e32 v144, v144
	v_rcp_f32_e32 v145, v145
	v_rcp_f32_e32 v146, v146
	v_rcp_f32_e32 v147, v147
	v_pk_mul_f32 v[140:141], v[132:133], v[140:141]
	v_pk_mul_f32 v[142:143], v[134:135], v[142:143]
	v_pk_mul_f32 v[144:145], v[136:137], v[144:145]
	v_pk_mul_f32 v[146:147], v[138:139], v[146:147]
	v_cvt_pk_bf16_f32 v148, v140, v141
	v_cvt_pk_bf16_f32 v149, v142, v143
	v_cvt_pk_bf16_f32 v150, v144, v145
	v_cvt_pk_bf16_f32 v151, v146, v147
	global_store_dwordx4 v5, v[148:151], s[30:31]
	s_add_u32 s30, s30, 0x1800
	s_addc_u32 s31, s31, 0
	v_pk_mul_f32 v[170:171], v[140:141], v[154:155] op_sel:[0,0] op_sel_hi:[1,0]
	v_pk_mul_f32 v[178:179], v[140:141], v[162:163] op_sel:[0,0] op_sel_hi:[1,0]
	v_pk_mul_f32 v[172:173], v[142:143], v[154:155] op_sel:[0,0] op_sel_hi:[1,0]
	v_pk_mul_f32 v[180:181], v[142:143], v[162:163] op_sel:[0,0] op_sel_hi:[1,0]
	v_pk_mul_f32 v[174:175], v[144:145], v[154:155] op_sel:[0,0] op_sel_hi:[1,0]
	v_pk_mul_f32 v[182:183], v[144:145], v[162:163] op_sel:[0,0] op_sel_hi:[1,0]
	v_pk_mul_f32 v[176:177], v[146:147], v[154:155] op_sel:[0,0] op_sel_hi:[1,0]
	v_pk_mul_f32 v[184:185], v[146:147], v[162:163] op_sel:[0,0] op_sel_hi:[1,0]
	v_lshlrev_b32_e32 v116, 16, v80
	v_and_b32_e32 v117, 0xffff0000, v80
	v_lshlrev_b32_e32 v118, 16, v81
	v_and_b32_e32 v119, 0xffff0000, v81
	v_lshlrev_b32_e32 v120, 16, v82
	v_and_b32_e32 v121, 0xffff0000, v82
	v_lshlrev_b32_e32 v122, 16, v83
	v_and_b32_e32 v123, 0xffff0000, v83
	v_pk_mul_f32 v[132:133], v[124:125], v[16:17]
	v_pk_fma_f32 v[132:133], v[100:101], v[24:25], v[132:133]
	v_pk_fma_f32 v[132:133], v[108:109], v[32:33], v[132:133]
	v_pk_fma_f32 v[132:133], v[116:117], v[40:41], v[132:133]
	v_pk_add_f32 v[132:133], v[132:133], v[48:49]
	v_pk_mul_f32 v[134:135], v[126:127], v[18:19]
	v_pk_fma_f32 v[134:135], v[102:103], v[26:27], v[134:135]
	v_pk_fma_f32 v[134:135], v[110:111], v[34:35], v[134:135]
	v_pk_fma_f32 v[134:135], v[118:119], v[42:43], v[134:135]
	v_pk_add_f32 v[134:135], v[134:135], v[50:51]
	v_pk_mul_f32 v[136:137], v[128:129], v[20:21]
	v_pk_fma_f32 v[136:137], v[104:105], v[28:29], v[136:137]
	v_pk_fma_f32 v[136:137], v[112:113], v[36:37], v[136:137]
	v_pk_fma_f32 v[136:137], v[120:121], v[44:45], v[136:137]
	v_pk_add_f32 v[136:137], v[136:137], v[52:53]
	v_pk_mul_f32 v[138:139], v[130:131], v[22:23]
	v_pk_fma_f32 v[138:139], v[106:107], v[30:31], v[138:139]
	v_pk_fma_f32 v[138:139], v[114:115], v[38:39], v[138:139]
	v_pk_fma_f32 v[138:139], v[122:123], v[46:47], v[138:139]
	v_pk_add_f32 v[138:139], v[138:139], v[54:55]
	v_pk_mul_f32 v[140:141], v[132:133], v[12:13] op_sel:[0,0] op_sel_hi:[1,0]
	v_pk_mul_f32 v[142:143], v[134:135], v[12:13] op_sel:[0,0] op_sel_hi:[1,0]
	v_pk_mul_f32 v[144:145], v[136:137], v[12:13] op_sel:[0,0] op_sel_hi:[1,0]
	v_pk_mul_f32 v[146:147], v[138:139], v[12:13] op_sel:[0,0] op_sel_hi:[1,0]
	v_exp_f32_e32 v140, v140
	v_exp_f32_e32 v141, v141
	v_exp_f32_e32 v142, v142
	v_exp_f32_e32 v143, v143
	v_exp_f32_e32 v144, v144
	v_exp_f32_e32 v145, v145
	v_exp_f32_e32 v146, v146
	v_exp_f32_e32 v147, v147
	v_pk_add_f32 v[140:141], v[140:141], v[12:13] op_sel:[0,1] op_sel_hi:[1,1]
	v_pk_add_f32 v[142:143], v[142:143], v[12:13] op_sel:[0,1] op_sel_hi:[1,1]
	v_pk_add_f32 v[144:145], v[144:145], v[12:13] op_sel:[0,1] op_sel_hi:[1,1]
	v_pk_add_f32 v[146:147], v[146:147], v[12:13] op_sel:[0,1] op_sel_hi:[1,1]
	v_rcp_f32_e32 v140, v140
	v_rcp_f32_e32 v141, v141
	v_rcp_f32_e32 v142, v142
	v_rcp_f32_e32 v143, v143
	v_rcp_f32_e32 v144, v144
	v_rcp_f32_e32 v145, v145
	v_rcp_f32_e32 v146, v146
	v_rcp_f32_e32 v147, v147
	v_pk_mul_f32 v[140:141], v[132:133], v[140:141]
	v_pk_mul_f32 v[142:143], v[134:135], v[142:143]
	v_pk_mul_f32 v[144:145], v[136:137], v[144:145]
	v_pk_mul_f32 v[146:147], v[138:139], v[146:147]
	v_cvt_pk_bf16_f32 v148, v140, v141
	v_cvt_pk_bf16_f32 v149, v142, v143
	v_cvt_pk_bf16_f32 v150, v144, v145
	v_cvt_pk_bf16_f32 v151, v146, v147
	global_store_dwordx4 v5, v[148:151], s[30:31]
	s_add_u32 s30, s30, 0x1800
	s_addc_u32 s31, s31, 0
	v_pk_mul_f32 v[132:133], v[140:141], v[154:155] op_sel:[0,1] op_sel_hi:[1,1]
	v_pk_mul_f32 v[56:57], v[140:141], v[162:163] op_sel:[0,1] op_sel_hi:[1,1]
	v_pk_mul_f32 v[134:135], v[142:143], v[154:155] op_sel:[0,1] op_sel_hi:[1,1]
	v_pk_mul_f32 v[58:59], v[142:143], v[162:163] op_sel:[0,1] op_sel_hi:[1,1]
	v_pk_mul_f32 v[136:137], v[144:145], v[154:155] op_sel:[0,1] op_sel_hi:[1,1]
	v_pk_mul_f32 v[60:61], v[144:145], v[162:163] op_sel:[0,1] op_sel_hi:[1,1]
	v_pk_mul_f32 v[138:139], v[146:147], v[154:155] op_sel:[0,1] op_sel_hi:[1,1]
	v_pk_mul_f32 v[62:63], v[146:147], v[162:163] op_sel:[0,1] op_sel_hi:[1,1]
	v_cvt_pk_bf16_f32 v215, v170, v132
	v_cvt_pk_bf16_f32 v187, v178, v56
	v_cvt_pk_bf16_f32 v219, v171, v133
	v_cvt_pk_bf16_f32 v191, v179, v57
	v_cvt_pk_bf16_f32 v223, v172, v134
; __device__ __forceinline__ unsigned pk2(float lo, float hi) { unsigned r; asm("v_cvt_pk_bf16_f32 %0, %1, %2" : "=v"(r) : "v"(lo), "v"(hi)); return r; }
; __device__ __forceinline__ float siluf_(float x) { return x * __builtin_amdgcn_rcpf(1.f + __expf(-x)); }
; __device__ __forceinline__ void ssdconv_prompt_item(const bf16_t* PROJ, int row0, bool has_hist, int cgi, const float* w, const float* bias, bf16_t* XBC, float* state_out,
;                                                     const float* DT, const float* CS, bf16_t* XT1, bf16_t* XT2, bf16_t* BT) {
;     ...
;     for (int t = 0; t < 8; ++t) {
;         float cur[8];
;         unpack8(rows[t], cur);
; #pragma unroll
;         for (int e = 0; e < 8; ++e) { float v = h0[e] * wv[0][e] + h1[e] * wv[1][e] + h2[e] * wv[2][e] + cur[e] * wv[3][e] + bv[e]; o[t][e] = siluf_(v); h0[e] = h1[e]; h1[e] = h2[e]; h2[e] = cur[e]; }
;         *(u32x4*)(XBC + (size_t)(row0 + t) * XBCW + c0) = pack8(o[t]);
;     }
;     if (state_out) {
;         *(f32x4*)(state_out + 0 * XBCW + c0) = (f32x4){h0[0], h0[1], h0[2], h0[3]}; *(f32x4*)(state_out + 0 * XBCW + c0 + 4) = (f32x4){h0[4], h0[5], h0[6], h0[7]};
;         *(f32x4*)(state_out + 1 * XBCW + c0) = (f32x4){h1[0], h1[1], h1[2], h1[3]}; *(f32x4*)(state_out + 1 * XBCW + c0 + 4) = (f32x4){h1[4], h1[5], h1[6], h1[7]};
;         *(f32x4*)(state_out + 2 * XBCW + c0) = (f32x4){h2[0], h2[1], h2[2], h2[3]}; *(f32x4*)(state_out + 2 * XBCW + c0 + 4) = (f32x4){h2[4], h2[5], h2[6], h2[7]};
;     }
;     const int chunk = row0 >> 7, jb = row0 & 127;
;     if (isx) {
; #pragma unroll
;         for (int e = 0; e < 8; ++e) { u32x4 a, b2;
;             a.x = pk2(o[0][e] * f1[0], o[1][e] * f1[1]); a.y = pk2(o[2][e] * f1[2], o[3][e] * f1[3]); a.z = pk2(o[4][e] * f1[4], o[5][e] * f1[5]); a.w = pk2(o[6][e] * f1[6], o[7][e] * f1[7]);
;             b2.x = pk2(o[0][e] * f2[0], o[1][e] * f2[1]); b2.y = pk2(o[2][e] * f2[2], o[3][e] * f2[3]); b2.z = pk2(o[4][e] * f2[4], o[5][e] * f2[5]); b2.w = pk2(o[6][e] * f2[6], o[7][e] * f2[7]);
;             const size_t off = ((size_t)chunk * DM + c0 + e) * 128 + jb;
;             *(u32x4*)(XT1 + off) = a; *(u32x4*)(XT2 + off) = b2; }
	v_cvt_pk_bf16_f32 v195, v180, v58
	v_cvt_pk_bf16_f32 v227, v173, v135
	v_cvt_pk_bf16_f32 v199, v181, v59
	v_cvt_pk_bf16_f32 v231, v174, v136
	v_cvt_pk_bf16_f32 v203, v182, v60
	v_cvt_pk_bf16_f32 v235, v175, v137
	v_cvt_pk_bf16_f32 v207, v183, v61
	v_cvt_pk_bf16_f32 v239, v176, v138
	v_cvt_pk_bf16_f32 v65, v184, v62
	v_cvt_pk_bf16_f32 v243, v177, v139
	v_cvt_pk_bf16_f32 v249, v185, v63
	v_lshlrev_b32_e32 v124, 16, v84
	v_and_b32_e32 v125, 0xffff0000, v84
	v_lshlrev_b32_e32 v126, 16, v85
	v_and_b32_e32 v127, 0xffff0000, v85
	v_lshlrev_b32_e32 v128, 16, v86
	v_and_b32_e32 v129, 0xffff0000, v86
	v_lshlrev_b32_e32 v130, 16, v87
	v_and_b32_e32 v131, 0xffff0000, v87
	v_pk_mul_f32 v[132:133], v[100:101], v[16:17]
	v_pk_fma_f32 v[132:133], v[108:109], v[24:25], v[132:133]
	v_pk_fma_f32 v[132:133], v[116:117], v[32:33], v[132:133]
	v_pk_fma_f32 v[132:133], v[124:125], v[40:41], v[132:133]
	v_pk_add_f32 v[132:133], v[132:133], v[48:49]
	v_pk_mul_f32 v[134:135], v[102:103], v[18:19]
	v_pk_fma_f32 v[134:135], v[110:111], v[26:27], v[134:135]
	v_pk_fma_f32 v[134:135], v[118:119], v[34:35], v[134:135]
	v_pk_fma_f32 v[134:135], v[126:127], v[42:43], v[134:135]
	v_pk_add_f32 v[134:135], v[134:135], v[50:51]
	v_pk_mul_f32 v[136:137], v[104:105], v[20:21]
	v_pk_fma_f32 v[136:137], v[112:113], v[28:29], v[136:137]
	v_pk_fma_f32 v[136:137], v[120:121], v[36:37], v[136:137]
	v_pk_fma_f32 v[136:137], v[128:129], v[44:45], v[136:137]
	v_pk_add_f32 v[136:137], v[136:137], v[52:53]
	v_pk_mul_f32 v[138:139], v[106:107], v[22:23]
	v_pk_fma_f32 v[138:139], v[114:115], v[30:31], v[138:139]
	v_pk_fma_f32 v[138:139], v[122:123], v[38:39], v[138:139]
	v_pk_fma_f32 v[138:139], v[130:131], v[46:47], v[138:139]
	v_pk_add_f32 v[138:139], v[138:139], v[54:55]
	v_pk_mul_f32 v[140:141], v[132:133], v[12:13] op_sel:[0,0] op_sel_hi:[1,0]
	v_pk_mul_f32 v[142:143], v[134:135], v[12:13] op_sel:[0,0] op_sel_hi:[1,0]
	v_pk_mul_f32 v[144:145], v[136:137], v[12:13] op_sel:[0,0] op_sel_hi:[1,0]
	v_pk_mul_f32 v[146:147], v[138:139], v[12:13] op_sel:[0,0] op_sel_hi:[1,0]
	v_exp_f32_e32 v140, v140
	v_exp_f32_e32 v141, v141
	v_exp_f32_e32 v142, v142
	v_exp_f32_e32 v143, v143
	v_exp_f32_e32 v144, v144
	v_exp_f32_e32 v145, v145
	v_exp_f32_e32 v146, v146
	v_exp_f32_e32 v147, v147
	v_pk_add_f32 v[140:141], v[140:141], v[12:13] op_sel:[0,1] op_sel_hi:[1,1]
	v_pk_add_f32 v[142:143], v[142:143], v[12:13] op_sel:[0,1] op_sel_hi:[1,1]
	v_pk_add_f32 v[144:145], v[144:145], v[12:13] op_sel:[0,1] op_sel_hi:[1,1]
	v_pk_add_f32 v[146:147], v[146:147], v[12:13] op_sel:[0,1] op_sel_hi:[1,1]
	v_rcp_f32_e32 v140, v140
	v_rcp_f32_e32 v141, v141
	v_rcp_f32_e32 v142, v142
	v_rcp_f32_e32 v143, v143
	v_rcp_f32_e32 v144, v144
	v_rcp_f32_e32 v145, v145
	v_rcp_f32_e32 v146, v146
	v_rcp_f32_e32 v147, v147
	v_pk_mul_f32 v[140:141], v[132:133], v[140:141]
	v_pk_mul_f32 v[142:143], v[134:135], v[142:143]
	v_pk_mul_f32 v[144:145], v[136:137], v[144:145]
	v_pk_mul_f32 v[146:147], v[138:139], v[146:147]
	v_cvt_pk_bf16_f32 v148, v140, v141
	v_cvt_pk_bf16_f32 v149, v142, v143
	v_cvt_pk_bf16_f32 v150, v144, v145
	v_cvt_pk_bf16_f32 v151, v146, v147
	global_store_dwordx4 v5, v[148:151], s[30:31]
	s_add_u32 s30, s30, 0x1800
	s_addc_u32 s31, s31, 0
	v_pk_mul_f32 v[170:171], v[140:141], v[156:157] op_sel:[0,0] op_sel_hi:[1,0]
	v_pk_mul_f32 v[178:179], v[140:141], v[164:165] op_sel:[0,0] op_sel_hi:[1,0]
	v_pk_mul_f32 v[172:173], v[142:143], v[156:157] op_sel:[0,0] op_sel_hi:[1,0]
	v_pk_mul_f32 v[180:181], v[142:143], v[164:165] op_sel:[0,0] op_sel_hi:[1,0]
	v_pk_mul_f32 v[174:175], v[144:145], v[156:157] op_sel:[0,0] op_sel_hi:[1,0]
	v_pk_mul_f32 v[182:183], v[144:145], v[164:165] op_sel:[0,0] op_sel_hi:[1,0]
	v_pk_mul_f32 v[176:177], v[146:147], v[156:157] op_sel:[0,0] op_sel_hi:[1,0]
	v_pk_mul_f32 v[184:185], v[146:147], v[164:165] op_sel:[0,0] op_sel_hi:[1,0]
	v_lshlrev_b32_e32 v100, 16, v88
	v_and_b32_e32 v101, 0xffff0000, v88
	v_lshlrev_b32_e32 v102, 16, v89
	v_and_b32_e32 v103, 0xffff0000, v89
	v_lshlrev_b32_e32 v104, 16, v90
	v_and_b32_e32 v105, 0xffff0000, v90
	v_lshlrev_b32_e32 v106, 16, v91
	v_and_b32_e32 v107, 0xffff0000, v91
	v_pk_mul_f32 v[132:133], v[108:109], v[16:17]
	v_pk_fma_f32 v[132:133], v[116:117], v[24:25], v[132:133]
	v_pk_fma_f32 v[132:133], v[124:125], v[32:33], v[132:133]
	v_pk_fma_f32 v[132:133], v[100:101], v[40:41], v[132:133]
	v_pk_add_f32 v[132:133], v[132:133], v[48:49]
	v_pk_mul_f32 v[134:135], v[110:111], v[18:19]
	v_pk_fma_f32 v[134:135], v[118:119], v[26:27], v[134:135]
	v_pk_fma_f32 v[134:135], v[126:127], v[34:35], v[134:135]
	v_pk_fma_f32 v[134:135], v[102:103], v[42:43], v[134:135]
	v_pk_add_f32 v[134:135], v[134:135], v[50:51]
	v_pk_mul_f32 v[136:137], v[112:113], v[20:21]
	v_pk_fma_f32 v[136:137], v[120:121], v[28:29], v[136:137]
	v_pk_fma_f32 v[136:137], v[128:129], v[36:37], v[136:137]
	v_pk_fma_f32 v[136:137], v[104:105], v[44:45], v[136:137]
	v_pk_add_f32 v[136:137], v[136:137], v[52:53]
	v_pk_mul_f32 v[138:139], v[114:115], v[22:23]
	v_pk_fma_f32 v[138:139], v[122:123], v[30:31], v[138:139]
	v_pk_fma_f32 v[138:139], v[130:131], v[38:39], v[138:139]
	v_pk_fma_f32 v[138:139], v[106:107], v[46:47], v[138:139]
	v_pk_add_f32 v[138:139], v[138:139], v[54:55]
	v_pk_mul_f32 v[140:141], v[132:133], v[12:13] op_sel:[0,0] op_sel_hi:[1,0]
	v_pk_mul_f32 v[142:143], v[134:135], v[12:13] op_sel:[0,0] op_sel_hi:[1,0]
	v_pk_mul_f32 v[144:145], v[136:137], v[12:13] op_sel:[0,0] op_sel_hi:[1,0]
	v_pk_mul_f32 v[146:147], v[138:139], v[12:13] op_sel:[0,0] op_sel_hi:[1,0]
	v_exp_f32_e32 v140, v140
	v_exp_f32_e32 v141, v141
	v_exp_f32_e32 v142, v142
	v_exp_f32_e32 v143, v143
	v_exp_f32_e32 v144, v144
; __device__ __forceinline__ unsigned pk2(float lo, float hi) { unsigned r; asm("v_cvt_pk_bf16_f32 %0, %1, %2" : "=v"(r) : "v"(lo), "v"(hi)); return r; }
; __device__ __forceinline__ float siluf_(float x) { return x * __builtin_amdgcn_rcpf(1.f + __expf(-x)); }
; __device__ __forceinline__ void ssdconv_prompt_item(const bf16_t* PROJ, int row0, bool has_hist, int cgi, const float* w, const float* bias, bf16_t* XBC, float* state_out,
;                                                     const float* DT, const float* CS, bf16_t* XT1, bf16_t* XT2, bf16_t* BT) {
;     ...
;     for (int t = 0; t < 8; ++t) {
;         float cur[8];
;         unpack8(rows[t], cur);
; #pragma unroll
;         for (int e = 0; e < 8; ++e) { float v = h0[e] * wv[0][e] + h1[e] * wv[1][e] + h2[e] * wv[2][e] + cur[e] * wv[3][e] + bv[e]; o[t][e] = siluf_(v); h0[e] = h1[e]; h1[e] = h2[e]; h2[e] = cur[e]; }
;         *(u32x4*)(XBC + (size_t)(row0 + t) * XBCW + c0) = pack8(o[t]);
;     }
;     if (state_out) {
;         *(f32x4*)(state_out + 0 * XBCW + c0) = (f32x4){h0[0], h0[1], h0[2], h0[3]}; *(f32x4*)(state_out + 0 * XBCW + c0 + 4) = (f32x4){h0[4], h0[5], h0[6], h0[7]};
;         *(f32x4*)(state_out + 1 * XBCW + c0) = (f32x4){h1[0], h1[1], h1[2], h1[3]}; *(f32x4*)(state_out + 1 * XBCW + c0 + 4) = (f32x4){h1[4], h1[5], h1[6], h1[7]};
;         *(f32x4*)(state_out + 2 * XBCW + c0) = (f32x4){h2[0], h2[1], h2[2], h2[3]}; *(f32x4*)(state_out + 2 * XBCW + c0 + 4) = (f32x4){h2[4], h2[5], h2[6], h2[7]};
;     }
;     const int chunk = row0 >> 7, jb = row0 & 127;
;     if (isx) {
; #pragma unroll
;         for (int e = 0; e < 8; ++e) { u32x4 a, b2;
;             a.x = pk2(o[0][e] * f1[0], o[1][e] * f1[1]); a.y = pk2(o[2][e] * f1[2], o[3][e] * f1[3]); a.z = pk2(o[4][e] * f1[4], o[5][e] * f1[5]); a.w = pk2(o[6][e] * f1[6], o[7][e] * f1[7]);
;             b2.x = pk2(o[0][e] * f2[0], o[1][e] * f2[1]); b2.y = pk2(o[2][e] * f2[2], o[3][e] * f2[3]); b2.z = pk2(o[4][e] * f2[4], o[5][e] * f2[5]); b2.w = pk2(o[6][e] * f2[6], o[7][e] * f2[7]);
;             const size_t off = ((size_t)chunk * DM + c0 + e) * 128 + jb;
;             *(u32x4*)(XT1 + off) = a; *(u32x4*)(XT2 + off) = b2; }
	v_exp_f32_e32 v145, v145
	v_exp_f32_e32 v146, v146
	v_exp_f32_e32 v147, v147
	v_pk_add_f32 v[140:141], v[140:141], v[12:13] op_sel:[0,1] op_sel_hi:[1,1]
	v_pk_add_f32 v[142:143], v[142:143], v[12:13] op_sel:[0,1] op_sel_hi:[1,1]
	v_pk_add_f32 v[144:145], v[144:145], v[12:13] op_sel:[0,1] op_sel_hi:[1,1]
	v_pk_add_f32 v[146:147], v[146:147], v[12:13] op_sel:[0,1] op_sel_hi:[1,1]
	v_rcp_f32_e32 v140, v140
	v_rcp_f32_e32 v141, v141
	v_rcp_f32_e32 v142, v142
	v_rcp_f32_e32 v143, v143
	v_rcp_f32_e32 v144, v144
	v_rcp_f32_e32 v145, v145
	v_rcp_f32_e32 v146, v146
	v_rcp_f32_e32 v147, v147
	v_pk_mul_f32 v[140:141], v[132:133], v[140:141]
	v_pk_mul_f32 v[142:143], v[134:135], v[142:143]
	v_pk_mul_f32 v[144:145], v[136:137], v[144:145]
	v_pk_mul_f32 v[146:147], v[138:139], v[146:147]
	v_cvt_pk_bf16_f32 v148, v140, v141
	v_cvt_pk_bf16_f32 v149, v142, v143
	v_cvt_pk_bf16_f32 v150, v144, v145
	v_cvt_pk_bf16_f32 v151, v146, v147
	global_store_dwordx4 v5, v[148:151], s[30:31]
	s_add_u32 s30, s30, 0x1800
	s_addc_u32 s31, s31, 0
	v_pk_mul_f32 v[132:133], v[140:141], v[156:157] op_sel:[0,1] op_sel_hi:[1,1]
	v_pk_mul_f32 v[56:57], v[140:141], v[164:165] op_sel:[0,1] op_sel_hi:[1,1]
	v_pk_mul_f32 v[134:135], v[142:143], v[156:157] op_sel:[0,1] op_sel_hi:[1,1]
	v_pk_mul_f32 v[58:59], v[142:143], v[164:165] op_sel:[0,1] op_sel_hi:[1,1]
	v_pk_mul_f32 v[136:137], v[144:145], v[156:157] op_sel:[0,1] op_sel_hi:[1,1]
	v_pk_mul_f32 v[60:61], v[144:145], v[164:165] op_sel:[0,1] op_sel_hi:[1,1]
	v_pk_mul_f32 v[138:139], v[146:147], v[156:157] op_sel:[0,1] op_sel_hi:[1,1]
	v_pk_mul_f32 v[62:63], v[146:147], v[164:165] op_sel:[0,1] op_sel_hi:[1,1]
	v_cvt_pk_bf16_f32 v216, v170, v132
	v_cvt_pk_bf16_f32 v188, v178, v56
	v_cvt_pk_bf16_f32 v220, v171, v133
	v_cvt_pk_bf16_f32 v192, v179, v57
	v_cvt_pk_bf16_f32 v224, v172, v134
	v_cvt_pk_bf16_f32 v196, v180, v58
	v_cvt_pk_bf16_f32 v228, v173, v135
	v_cvt_pk_bf16_f32 v200, v181, v59
	v_cvt_pk_bf16_f32 v232, v174, v136
	v_cvt_pk_bf16_f32 v204, v182, v60
	v_cvt_pk_bf16_f32 v236, v175, v137
	v_cvt_pk_bf16_f32 v208, v183, v61
	v_cvt_pk_bf16_f32 v240, v176, v138
	v_cvt_pk_bf16_f32 v66, v184, v62
	v_cvt_pk_bf16_f32 v244, v177, v139
	v_cvt_pk_bf16_f32 v250, v185, v63
	v_lshlrev_b32_e32 v108, 16, v92
	v_and_b32_e32 v109, 0xffff0000, v92
	v_lshlrev_b32_e32 v110, 16, v93
	v_and_b32_e32 v111, 0xffff0000, v93
	v_lshlrev_b32_e32 v112, 16, v94
	v_and_b32_e32 v113, 0xffff0000, v94
	v_lshlrev_b32_e32 v114, 16, v95
	v_and_b32_e32 v115, 0xffff0000, v95
	v_pk_mul_f32 v[132:133], v[116:117], v[16:17]
	v_pk_fma_f32 v[132:133], v[124:125], v[24:25], v[132:133]
	v_pk_fma_f32 v[132:133], v[100:101], v[32:33], v[132:133]
	v_pk_fma_f32 v[132:133], v[108:109], v[40:41], v[132:133]
	v_pk_add_f32 v[132:133], v[132:133], v[48:49]
	v_pk_mul_f32 v[134:135], v[118:119], v[18:19]
	v_pk_fma_f32 v[134:135], v[126:127], v[26:27], v[134:135]
	v_pk_fma_f32 v[134:135], v[102:103], v[34:35], v[134:135]
	v_pk_fma_f32 v[134:135], v[110:111], v[42:43], v[134:135]
	v_pk_add_f32 v[134:135], v[134:135], v[50:51]
	v_pk_mul_f32 v[136:137], v[120:121], v[20:21]
	v_pk_fma_f32 v[136:137], v[128:129], v[28:29], v[136:137]
	v_pk_fma_f32 v[136:137], v[104:105], v[36:37], v[136:137]
	v_pk_fma_f32 v[136:137], v[112:113], v[44:45], v[136:137]
	v_pk_add_f32 v[136:137], v[136:137], v[52:53]
	v_pk_mul_f32 v[138:139], v[122:123], v[22:23]
	v_pk_fma_f32 v[138:139], v[130:131], v[30:31], v[138:139]
	v_pk_fma_f32 v[138:139], v[106:107], v[38:39], v[138:139]
	v_pk_fma_f32 v[138:139], v[114:115], v[46:47], v[138:139]
	v_pk_add_f32 v[138:139], v[138:139], v[54:55]
	v_pk_mul_f32 v[140:141], v[132:133], v[12:13] op_sel:[0,0] op_sel_hi:[1,0]
	v_pk_mul_f32 v[142:143], v[134:135], v[12:13] op_sel:[0,0] op_sel_hi:[1,0]
	v_pk_mul_f32 v[144:145], v[136:137], v[12:13] op_sel:[0,0] op_sel_hi:[1,0]
	v_pk_mul_f32 v[146:147], v[138:139], v[12:13] op_sel:[0,0] op_sel_hi:[1,0]
	v_exp_f32_e32 v140, v140
	v_exp_f32_e32 v141, v141
	v_exp_f32_e32 v142, v142
	v_exp_f32_e32 v143, v143
	v_exp_f32_e32 v144, v144
	v_exp_f32_e32 v145, v145
	v_exp_f32_e32 v146, v146
	v_exp_f32_e32 v147, v147
	v_pk_add_f32 v[140:141], v[140:141], v[12:13] op_sel:[0,1] op_sel_hi:[1,1]
	v_pk_add_f32 v[142:143], v[142:143], v[12:13] op_sel:[0,1] op_sel_hi:[1,1]
	v_pk_add_f32 v[144:145], v[144:145], v[12:13] op_sel:[0,1] op_sel_hi:[1,1]
	v_pk_add_f32 v[146:147], v[146:147], v[12:13] op_sel:[0,1] op_sel_hi:[1,1]
	v_rcp_f32_e32 v140, v140
	v_rcp_f32_e32 v141, v141
	v_rcp_f32_e32 v142, v142
	v_rcp_f32_e32 v143, v143
	v_rcp_f32_e32 v144, v144
	v_rcp_f32_e32 v145, v145
	v_rcp_f32_e32 v146, v146
	v_rcp_f32_e32 v147, v147
	v_pk_mul_f32 v[140:141], v[132:133], v[140:141]
	v_pk_mul_f32 v[142:143], v[134:135], v[142:143]
	v_pk_mul_f32 v[144:145], v[136:137], v[144:145]
	v_pk_mul_f32 v[146:147], v[138:139], v[146:147]
	v_cvt_pk_bf16_f32 v148, v140, v141
	v_cvt_pk_bf16_f32 v149, v142, v143
	v_cvt_pk_bf16_f32 v150, v144, v145
	v_cvt_pk_bf16_f32 v151, v146, v147
	global_store_dwordx4 v5, v[148:151], s[30:31]
	s_add_u32 s30, s30, 0x1800
	s_addc_u32 s31, s31, 0
	v_pk_mul_f32 v[170:171], v[140:141], v[158:159] op_sel:[0,0] op_sel_hi:[1,0]
	v_pk_mul_f32 v[178:179], v[140:141], v[166:167] op_sel:[0,0] op_sel_hi:[1,0]
	v_pk_mul_f32 v[172:173], v[142:143], v[158:159] op_sel:[0,0] op_sel_hi:[1,0]
	v_pk_mul_f32 v[180:181], v[142:143], v[166:167] op_sel:[0,0] op_sel_hi:[1,0]
	v_pk_mul_f32 v[174:175], v[144:145], v[158:159] op_sel:[0,0] op_sel_hi:[1,0]
	v_pk_mul_f32 v[182:183], v[144:145], v[166:167] op_sel:[0,0] op_sel_hi:[1,0]
	v_pk_mul_f32 v[176:177], v[146:147], v[158:159] op_sel:[0,0] op_sel_hi:[1,0]
; __device__ __forceinline__ unsigned pk2(float lo, float hi) { unsigned r; asm("v_cvt_pk_bf16_f32 %0, %1, %2" : "=v"(r) : "v"(lo), "v"(hi)); return r; }
; __device__ __forceinline__ void ssdconv_prompt_item(const bf16_t* PROJ, int row0, bool has_hist, int cgi, const float* w, const float* bias, bf16_t* XBC, float* state_out,
;                                                     const float* DT, const float* CS, bf16_t* XT1, bf16_t* XT2, bf16_t* BT) {
;     ...
;     if (state_out) {
;         *(f32x4*)(state_out + 0 * XBCW + c0) = (f32x4){h0[0], h0[1], h0[2], h0[3]}; *(f32x4*)(state_out + 0 * XBCW + c0 + 4) = (f32x4){h0[4], h0[5], h0[6], h0[7]};
;         *(f32x4*)(state_out + 1 * XBCW + c0) = (f32x4){h1[0], h1[1], h1[2], h1[3]}; *(f32x4*)(state_out + 1 * XBCW + c0 + 4) = (f32x4){h1[4], h1[5], h1[6], h1[7]};
;         *(f32x4*)(state_out + 2 * XBCW + c0) = (f32x4){h2[0], h2[1], h2[2], h2[3]}; *(f32x4*)(state_out + 2 * XBCW + c0 + 4) = (f32x4){h2[4], h2[5], h2[6], h2[7]};
;     ...
;     if (isx) {
; #pragma unroll
;         for (int e = 0; e < 8; ++e) { u32x4 a, b2;
;             a.x = pk2(o[0][e] * f1[0], o[1][e] * f1[1]); a.y = pk2(o[2][e] * f1[2], o[3][e] * f1[3]); a.z = pk2(o[4][e] * f1[4], o[5][e] * f1[5]); a.w = pk2(o[6][e] * f1[6], o[7][e] * f1[7]);
;             b2.x = pk2(o[0][e] * f2[0], o[1][e] * f2[1]); b2.y = pk2(o[2][e] * f2[2], o[3][e] * f2[3]); b2.z = pk2(o[4][e] * f2[4], o[5][e] * f2[5]); b2.w = pk2(o[6][e] * f2[6], o[7][e] * f2[7]);
;             const size_t off = ((size_t)chunk * DM + c0 + e) * 128 + jb;
;             *(u32x4*)(XT1 + off) = a; *(u32x4*)(XT2 + off) = b2; }
	v_pk_mul_f32 v[184:185], v[146:147], v[166:167] op_sel:[0,0] op_sel_hi:[1,0]
	v_lshlrev_b32_e32 v116, 16, v96
	v_and_b32_e32 v117, 0xffff0000, v96
	v_lshlrev_b32_e32 v118, 16, v97
	v_and_b32_e32 v119, 0xffff0000, v97
	v_lshlrev_b32_e32 v120, 16, v98
	v_and_b32_e32 v121, 0xffff0000, v98
	v_lshlrev_b32_e32 v122, 16, v99
	v_and_b32_e32 v123, 0xffff0000, v99
	v_pk_mul_f32 v[132:133], v[124:125], v[16:17]
	v_pk_fma_f32 v[132:133], v[100:101], v[24:25], v[132:133]
	v_pk_fma_f32 v[132:133], v[108:109], v[32:33], v[132:133]
	v_pk_fma_f32 v[132:133], v[116:117], v[40:41], v[132:133]
	v_pk_add_f32 v[132:133], v[132:133], v[48:49]
	v_pk_mul_f32 v[134:135], v[126:127], v[18:19]
	v_pk_fma_f32 v[134:135], v[102:103], v[26:27], v[134:135]
	v_pk_fma_f32 v[134:135], v[110:111], v[34:35], v[134:135]
	v_pk_fma_f32 v[134:135], v[118:119], v[42:43], v[134:135]
	v_pk_add_f32 v[134:135], v[134:135], v[50:51]
	v_pk_mul_f32 v[136:137], v[128:129], v[20:21]
	v_pk_fma_f32 v[136:137], v[104:105], v[28:29], v[136:137]
	v_pk_fma_f32 v[136:137], v[112:113], v[36:37], v[136:137]
	v_pk_fma_f32 v[136:137], v[120:121], v[44:45], v[136:137]
	v_pk_add_f32 v[136:137], v[136:137], v[52:53]
	v_pk_mul_f32 v[138:139], v[130:131], v[22:23]
	v_pk_fma_f32 v[138:139], v[106:107], v[30:31], v[138:139]
	v_pk_fma_f32 v[138:139], v[114:115], v[38:39], v[138:139]
	v_pk_fma_f32 v[138:139], v[122:123], v[46:47], v[138:139]
	v_pk_add_f32 v[138:139], v[138:139], v[54:55]
	v_pk_mul_f32 v[140:141], v[132:133], v[12:13] op_sel:[0,0] op_sel_hi:[1,0]
	v_pk_mul_f32 v[142:143], v[134:135], v[12:13] op_sel:[0,0] op_sel_hi:[1,0]
	v_pk_mul_f32 v[144:145], v[136:137], v[12:13] op_sel:[0,0] op_sel_hi:[1,0]
	v_pk_mul_f32 v[146:147], v[138:139], v[12:13] op_sel:[0,0] op_sel_hi:[1,0]
	v_exp_f32_e32 v140, v140
	v_exp_f32_e32 v141, v141
	v_exp_f32_e32 v142, v142
	v_exp_f32_e32 v143, v143
	v_exp_f32_e32 v144, v144
	v_exp_f32_e32 v145, v145
	v_exp_f32_e32 v146, v146
	v_exp_f32_e32 v147, v147
	v_pk_add_f32 v[140:141], v[140:141], v[12:13] op_sel:[0,1] op_sel_hi:[1,1]
	v_pk_add_f32 v[142:143], v[142:143], v[12:13] op_sel:[0,1] op_sel_hi:[1,1]
	v_pk_add_f32 v[144:145], v[144:145], v[12:13] op_sel:[0,1] op_sel_hi:[1,1]
	v_pk_add_f32 v[146:147], v[146:147], v[12:13] op_sel:[0,1] op_sel_hi:[1,1]
	v_rcp_f32_e32 v140, v140
	v_rcp_f32_e32 v141, v141
	v_rcp_f32_e32 v142, v142
	v_rcp_f32_e32 v143, v143
	v_rcp_f32_e32 v144, v144
	v_rcp_f32_e32 v145, v145
	v_rcp_f32_e32 v146, v146
	v_rcp_f32_e32 v147, v147
	v_pk_mul_f32 v[140:141], v[132:133], v[140:141]
	v_pk_mul_f32 v[142:143], v[134:135], v[142:143]
	v_pk_mul_f32 v[144:145], v[136:137], v[144:145]
	v_pk_mul_f32 v[146:147], v[138:139], v[146:147]
	v_cvt_pk_bf16_f32 v148, v140, v141
	v_cvt_pk_bf16_f32 v149, v142, v143
	v_cvt_pk_bf16_f32 v150, v144, v145
	v_cvt_pk_bf16_f32 v151, v146, v147
	global_store_dwordx4 v5, v[148:151], s[30:31]
	v_pk_mul_f32 v[132:133], v[140:141], v[158:159] op_sel:[0,1] op_sel_hi:[1,1]
	v_pk_mul_f32 v[56:57], v[140:141], v[166:167] op_sel:[0,1] op_sel_hi:[1,1]
	v_pk_mul_f32 v[134:135], v[142:143], v[158:159] op_sel:[0,1] op_sel_hi:[1,1]
	v_pk_mul_f32 v[58:59], v[142:143], v[166:167] op_sel:[0,1] op_sel_hi:[1,1]
	v_pk_mul_f32 v[136:137], v[144:145], v[158:159] op_sel:[0,1] op_sel_hi:[1,1]
	v_pk_mul_f32 v[60:61], v[144:145], v[166:167] op_sel:[0,1] op_sel_hi:[1,1]
	v_pk_mul_f32 v[138:139], v[146:147], v[158:159] op_sel:[0,1] op_sel_hi:[1,1]
	v_pk_mul_f32 v[62:63], v[146:147], v[166:167] op_sel:[0,1] op_sel_hi:[1,1]
	v_cvt_pk_bf16_f32 v217, v170, v132
	v_cvt_pk_bf16_f32 v189, v178, v56
	v_cvt_pk_bf16_f32 v221, v171, v133
	v_cvt_pk_bf16_f32 v193, v179, v57
	v_cvt_pk_bf16_f32 v225, v172, v134
	v_cvt_pk_bf16_f32 v197, v180, v58
	v_cvt_pk_bf16_f32 v229, v173, v135
	v_cvt_pk_bf16_f32 v201, v181, v59
	v_cvt_pk_bf16_f32 v233, v174, v136
	v_cvt_pk_bf16_f32 v205, v182, v60
	v_cvt_pk_bf16_f32 v237, v175, v137
	v_cvt_pk_bf16_f32 v209, v183, v61
	v_cvt_pk_bf16_f32 v241, v176, v138
	v_cvt_pk_bf16_f32 v67, v184, v62
	v_cvt_pk_bf16_f32 v245, v177, v139
	v_cvt_pk_bf16_f32 v251, v185, v63
	global_store_dwordx4 v8, v[214:217], s[34:35] offset:0
	global_store_dwordx4 v8, v[186:189], s[36:37] offset:0
	global_store_dwordx4 v8, v[218:221], s[34:35] offset:256
	global_store_dwordx4 v8, v[190:193], s[36:37] offset:256
	global_store_dwordx4 v8, v[222:225], s[34:35] offset:512
	global_store_dwordx4 v8, v[194:197], s[36:37] offset:512
	global_store_dwordx4 v8, v[226:229], s[34:35] offset:768
	global_store_dwordx4 v8, v[198:201], s[36:37] offset:768
	global_store_dwordx4 v8, v[230:233], s[34:35] offset:1024
	global_store_dwordx4 v8, v[202:205], s[36:37] offset:1024
	global_store_dwordx4 v8, v[234:237], s[34:35] offset:1280
	global_store_dwordx4 v8, v[206:209], s[36:37] offset:1280
	global_store_dwordx4 v8, v[238:241], s[34:35] offset:1536
	global_store_dwordx4 v8, v[64:67], s[36:37] offset:1536
	global_store_dwordx4 v8, v[242:245], s[34:35] offset:1792
	global_store_dwordx4 v8, v[248:251], s[36:37] offset:1792
	s_and_b32 s33, s5, 31
	s_cmp_eq_u32 s33, 31
	s_cbranch_scc0 .Lp2b_nostate_x
	s_mov_b64 s[48:49], exec
	s_and_b64 exec, exec, s[46:47]
	global_store_dwordx4 v11, v[100:103], s[38:39]
	global_store_dwordx4 v11, v[104:107], s[38:39] offset:16
	s_add_u32 s38, s38, 0x3000
	s_addc_u32 s39, s39, 0
	global_store_dwordx4 v11, v[108:111], s[38:39]
	global_store_dwordx4 v11, v[112:115], s[38:39] offset:16
	s_add_u32 s38, s38, 0x3000
	s_addc_u32 s39, s39, 0
	global_store_dwordx4 v11, v[116:119], s[38:39]
	global_store_dwordx4 v11, v[120:123], s[38:39] offset:16
	s_mov_b64 exec, s[48:49]

; __device__ __forceinline__ unsigned pk2(float lo, float hi) { unsigned r; asm("v_cvt_pk_bf16_f32 %0, %1, %2" : "=v"(r) : "v"(lo), "v"(hi)); return r; }
; __device__ __forceinline__ float siluf_(float x) { return x * __builtin_amdgcn_rcpf(1.f + __expf(-x)); }
; __device__ __forceinline__ void ssdconv_prompt_item(const bf16_t* PROJ, int row0, bool has_hist, int cgi, const float* w, const float* bias, bf16_t* XBC, float* state_out,
;                                                     const float* DT, const float* CS, bf16_t* XT1, bf16_t* XT2, bf16_t* BT) {
;     ...
;     for (int t = 0; t < 8; ++t) {
;         float cur[8];
;         unpack8(rows[t], cur);
; #pragma unroll
;         for (int e = 0; e < 8; ++e) { float v = h0[e] * wv[0][e] + h1[e] * wv[1][e] + h2[e] * wv[2][e] + cur[e] * wv[3][e] + bv[e]; o[t][e] = siluf_(v); h0[e] = h1[e]; h1[e] = h2[e]; h2[e] = cur[e]; }
;         *(u32x4*)(XBC + (size_t)(row0 + t) * XBCW + c0) = pack8(o[t]);
;     ...
;     } else if (isb) {
; #pragma unroll
;         for (int e = 0; e < 8; ++e) { u32x4 a;
;             a.x = pk2(o[0][e], o[1][e]); a.y = pk2(o[2][e], o[3][e]); a.z = pk2(o[4][e], o[5][e]); a.w = pk2(o[6][e], o[7][e]);
;             *(u32x4*)(BT + ((size_t)chunk * 512 + (c0 - 2048) + e) * 128 + jb) = a; }
.Lp2b_notx:
	s_cmp_lt_u32 s8, 40
	s_cbranch_scc0 .Lp2b_c
	s_sub_u32 s11, s8, 32
	s_lshl_b32 s11, s11, 14
	s_add_u32 s34, s16, 0x2000000
	s_addc_u32 s35, s17, 0
	s_add_u32 s34, s34, s11
	s_addc_u32 s35, s35, 0
	s_waitcnt vmcnt(0)
	v_cndmask_b32_e64 v56, 0, v56, s[44:45]
	v_cndmask_b32_e64 v57, 0, v57, s[44:45]
	v_cndmask_b32_e64 v58, 0, v58, s[44:45]
	v_cndmask_b32_e64 v59, 0, v59, s[44:45]
	v_cndmask_b32_e64 v60, 0, v60, s[44:45]
	v_cndmask_b32_e64 v61, 0, v61, s[44:45]
	v_cndmask_b32_e64 v62, 0, v62, s[44:45]
	v_cndmask_b32_e64 v63, 0, v63, s[44:45]
	v_cndmask_b32_e64 v64, 0, v64, s[44:45]
	v_cndmask_b32_e64 v65, 0, v65, s[44:45]
	v_cndmask_b32_e64 v66, 0, v66, s[44:45]
	v_cndmask_b32_e64 v67, 0, v67, s[44:45]
	v_lshlrev_b32_e32 v100, 16, v56
	v_and_b32_e32 v101, 0xffff0000, v56
	v_lshlrev_b32_e32 v102, 16, v57
	v_and_b32_e32 v103, 0xffff0000, v57
	v_lshlrev_b32_e32 v104, 16, v58
	v_and_b32_e32 v105, 0xffff0000, v58
	v_lshlrev_b32_e32 v106, 16, v59
	v_and_b32_e32 v107, 0xffff0000, v59
	v_lshlrev_b32_e32 v108, 16, v60
	v_and_b32_e32 v109, 0xffff0000, v60
	v_lshlrev_b32_e32 v110, 16, v61
	v_and_b32_e32 v111, 0xffff0000, v61
	v_lshlrev_b32_e32 v112, 16, v62
	v_and_b32_e32 v113, 0xffff0000, v62
	v_lshlrev_b32_e32 v114, 16, v63
	v_and_b32_e32 v115, 0xffff0000, v63
	v_lshlrev_b32_e32 v116, 16, v64
	v_and_b32_e32 v117, 0xffff0000, v64
	v_lshlrev_b32_e32 v118, 16, v65
	v_and_b32_e32 v119, 0xffff0000, v65
	v_lshlrev_b32_e32 v120, 16, v66
	v_and_b32_e32 v121, 0xffff0000, v66
	v_lshlrev_b32_e32 v122, 16, v67
	v_and_b32_e32 v123, 0xffff0000, v67
	v_lshlrev_b32_e32 v124, 16, v68
	v_and_b32_e32 v125, 0xffff0000, v68
	v_lshlrev_b32_e32 v126, 16, v69
	v_and_b32_e32 v127, 0xffff0000, v69
	v_lshlrev_b32_e32 v128, 16, v70
	v_and_b32_e32 v129, 0xffff0000, v70
	v_lshlrev_b32_e32 v130, 16, v71
	v_and_b32_e32 v131, 0xffff0000, v71
	v_pk_mul_f32 v[132:133], v[100:101], v[16:17]
	v_pk_fma_f32 v[132:133], v[108:109], v[24:25], v[132:133]
	v_pk_fma_f32 v[132:133], v[116:117], v[32:33], v[132:133]
	v_pk_fma_f32 v[132:133], v[124:125], v[40:41], v[132:133]
	v_pk_add_f32 v[132:133], v[132:133], v[48:49]
	v_pk_mul_f32 v[134:135], v[102:103], v[18:19]
	v_pk_fma_f32 v[134:135], v[110:111], v[26:27], v[134:135]
	v_pk_fma_f32 v[134:135], v[118:119], v[34:35], v[134:135]
	v_pk_fma_f32 v[134:135], v[126:127], v[42:43], v[134:135]
	v_pk_add_f32 v[134:135], v[134:135], v[50:51]
	v_pk_mul_f32 v[136:137], v[104:105], v[20:21]
	v_pk_fma_f32 v[136:137], v[112:113], v[28:29], v[136:137]
	v_pk_fma_f32 v[136:137], v[120:121], v[36:37], v[136:137]
	v_pk_fma_f32 v[136:137], v[128:129], v[44:45], v[136:137]
	v_pk_add_f32 v[136:137], v[136:137], v[52:53]
	v_pk_mul_f32 v[138:139], v[106:107], v[22:23]
	v_pk_fma_f32 v[138:139], v[114:115], v[30:31], v[138:139]
	v_pk_fma_f32 v[138:139], v[122:123], v[38:39], v[138:139]
	v_pk_fma_f32 v[138:139], v[130:131], v[46:47], v[138:139]
	v_pk_add_f32 v[138:139], v[138:139], v[54:55]
	v_pk_mul_f32 v[140:141], v[132:133], v[12:13] op_sel:[0,0] op_sel_hi:[1,0]
	v_pk_mul_f32 v[142:143], v[134:135], v[12:13] op_sel:[0,0] op_sel_hi:[1,0]
	v_pk_mul_f32 v[144:145], v[136:137], v[12:13] op_sel:[0,0] op_sel_hi:[1,0]
	v_pk_mul_f32 v[146:147], v[138:139], v[12:13] op_sel:[0,0] op_sel_hi:[1,0]
	v_exp_f32_e32 v140, v140
	v_exp_f32_e32 v141, v141
	v_exp_f32_e32 v142, v142
	v_exp_f32_e32 v143, v143
	v_exp_f32_e32 v144, v144
	v_exp_f32_e32 v145, v145
	v_exp_f32_e32 v146, v146
	v_exp_f32_e32 v147, v147
	v_pk_add_f32 v[140:141], v[140:141], v[12:13] op_sel:[0,1] op_sel_hi:[1,1]
	v_pk_add_f32 v[142:143], v[142:143], v[12:13] op_sel:[0,1] op_sel_hi:[1,1]
	v_pk_add_f32 v[144:145], v[144:145], v[12:13] op_sel:[0,1] op_sel_hi:[1,1]
	v_pk_add_f32 v[146:147], v[146:147], v[12:13] op_sel:[0,1] op_sel_hi:[1,1]
	v_rcp_f32_e32 v140, v140
	v_rcp_f32_e32 v141, v141
	v_rcp_f32_e32 v142, v142
	v_rcp_f32_e32 v143, v143
	v_rcp_f32_e32 v144, v144
	v_rcp_f32_e32 v145, v145
	v_rcp_f32_e32 v146, v146
	v_rcp_f32_e32 v147, v147
	v_pk_mul_f32 v[140:141], v[132:133], v[140:141]
	v_pk_mul_f32 v[142:143], v[134:135], v[142:143]
	v_pk_mul_f32 v[144:145], v[136:137], v[144:145]
	v_pk_mul_f32 v[146:147], v[138:139], v[146:147]
	v_cvt_pk_bf16_f32 v148, v140, v141
	v_cvt_pk_bf16_f32 v149, v142, v143
	v_cvt_pk_bf16_f32 v150, v144, v145
	v_cvt_pk_bf16_f32 v151, v146, v147
	global_store_dwordx4 v5, v[148:151], s[30:31]
	s_add_u32 s30, s30, 0x1800
	s_addc_u32 s31, s31, 0
	v_mov_b32_e32 v170, v140
	v_mov_b32_e32 v171, v141
	v_mov_b32_e32 v172, v142
	v_mov_b32_e32 v173, v143
	v_mov_b32_e32 v174, v144
	v_mov_b32_e32 v175, v145
	v_mov_b32_e32 v176, v146
	v_mov_b32_e32 v177, v147
	v_lshlrev_b32_e32 v100, 16, v72
	v_and_b32_e32 v101, 0xffff0000, v72
	v_lshlrev_b32_e32 v102, 16, v73
	v_and_b32_e32 v103, 0xffff0000, v73
	v_lshlrev_b32_e32 v104, 16, v74
	v_and_b32_e32 v105, 0xffff0000, v74
	v_lshlrev_b32_e32 v106, 16, v75
	v_and_b32_e32 v107, 0xffff0000, v75
	v_pk_mul_f32 v[132:133], v[108:109], v[16:17]
	v_pk_fma_f32 v[132:133], v[116:117], v[24:25], v[132:133]
	v_pk_fma_f32 v[132:133], v[124:125], v[32:33], v[132:133]
	v_pk_fma_f32 v[132:133], v[100:101], v[40:41], v[132:133]
	v_pk_add_f32 v[132:133], v[132:133], v[48:49]
	v_pk_mul_f32 v[134:135], v[110:111], v[18:19]
	v_pk_fma_f32 v[134:135], v[118:119], v[26:27], v[134:135]
	v_pk_fma_f32 v[134:135], v[126:127], v[34:35], v[134:135]
	v_pk_fma_f32 v[134:135], v[102:103], v[42:43], v[134:135]
	v_pk_add_f32 v[134:135], v[134:135], v[50:51]
	v_pk_mul_f32 v[136:137], v[112:113], v[20:21]
	v_pk_fma_f32 v[136:137], v[120:121], v[28:29], v[136:137]
	v_pk_fma_f32 v[136:137], v[128:129], v[36:37], v[136:137]
	v_pk_fma_f32 v[136:137], v[104:105], v[44:45], v[136:137]
; __device__ __forceinline__ unsigned pk2(float lo, float hi) { unsigned r; asm("v_cvt_pk_bf16_f32 %0, %1, %2" : "=v"(r) : "v"(lo), "v"(hi)); return r; }
; __device__ __forceinline__ float siluf_(float x) { return x * __builtin_amdgcn_rcpf(1.f + __expf(-x)); }
; __device__ __forceinline__ void ssdconv_prompt_item(const bf16_t* PROJ, int row0, bool has_hist, int cgi, const float* w, const float* bias, bf16_t* XBC, float* state_out,
;                                                     const float* DT, const float* CS, bf16_t* XT1, bf16_t* XT2, bf16_t* BT) {
;     ...
;     for (int t = 0; t < 8; ++t) {
;         float cur[8];
;         unpack8(rows[t], cur);
; #pragma unroll
;         for (int e = 0; e < 8; ++e) { float v = h0[e] * wv[0][e] + h1[e] * wv[1][e] + h2[e] * wv[2][e] + cur[e] * wv[3][e] + bv[e]; o[t][e] = siluf_(v); h0[e] = h1[e]; h1[e] = h2[e]; h2[e] = cur[e]; }
;         *(u32x4*)(XBC + (size_t)(row0 + t) * XBCW + c0) = pack8(o[t]);
;     ...
;     } else if (isb) {
; #pragma unroll
;         for (int e = 0; e < 8; ++e) { u32x4 a;
;             a.x = pk2(o[0][e], o[1][e]); a.y = pk2(o[2][e], o[3][e]); a.z = pk2(o[4][e], o[5][e]); a.w = pk2(o[6][e], o[7][e]);
;             *(u32x4*)(BT + ((size_t)chunk * 512 + (c0 - 2048) + e) * 128 + jb) = a; }
	v_pk_add_f32 v[136:137], v[136:137], v[52:53]
	v_pk_mul_f32 v[138:139], v[114:115], v[22:23]
	v_pk_fma_f32 v[138:139], v[122:123], v[30:31], v[138:139]
	v_pk_fma_f32 v[138:139], v[130:131], v[38:39], v[138:139]
	v_pk_fma_f32 v[138:139], v[106:107], v[46:47], v[138:139]
	v_pk_add_f32 v[138:139], v[138:139], v[54:55]
	v_pk_mul_f32 v[140:141], v[132:133], v[12:13] op_sel:[0,0] op_sel_hi:[1,0]
	v_pk_mul_f32 v[142:143], v[134:135], v[12:13] op_sel:[0,0] op_sel_hi:[1,0]
	v_pk_mul_f32 v[144:145], v[136:137], v[12:13] op_sel:[0,0] op_sel_hi:[1,0]
	v_pk_mul_f32 v[146:147], v[138:139], v[12:13] op_sel:[0,0] op_sel_hi:[1,0]
	v_exp_f32_e32 v140, v140
	v_exp_f32_e32 v141, v141
	v_exp_f32_e32 v142, v142
	v_exp_f32_e32 v143, v143
	v_exp_f32_e32 v144, v144
	v_exp_f32_e32 v145, v145
	v_exp_f32_e32 v146, v146
	v_exp_f32_e32 v147, v147
	v_pk_add_f32 v[140:141], v[140:141], v[12:13] op_sel:[0,1] op_sel_hi:[1,1]
	v_pk_add_f32 v[142:143], v[142:143], v[12:13] op_sel:[0,1] op_sel_hi:[1,1]
	v_pk_add_f32 v[144:145], v[144:145], v[12:13] op_sel:[0,1] op_sel_hi:[1,1]
	v_pk_add_f32 v[146:147], v[146:147], v[12:13] op_sel:[0,1] op_sel_hi:[1,1]
	v_rcp_f32_e32 v140, v140
	v_rcp_f32_e32 v141, v141
	v_rcp_f32_e32 v142, v142
	v_rcp_f32_e32 v143, v143
	v_rcp_f32_e32 v144, v144
	v_rcp_f32_e32 v145, v145
	v_rcp_f32_e32 v146, v146
	v_rcp_f32_e32 v147, v147
	v_pk_mul_f32 v[140:141], v[132:133], v[140:141]
	v_pk_mul_f32 v[142:143], v[134:135], v[142:143]
	v_pk_mul_f32 v[144:145], v[136:137], v[144:145]
	v_pk_mul_f32 v[146:147], v[138:139], v[146:147]
	v_cvt_pk_bf16_f32 v148, v140, v141
	v_cvt_pk_bf16_f32 v149, v142, v143
	v_cvt_pk_bf16_f32 v150, v144, v145
	v_cvt_pk_bf16_f32 v151, v146, v147
	global_store_dwordx4 v5, v[148:151], s[30:31]
	s_add_u32 s30, s30, 0x1800
	s_addc_u32 s31, s31, 0
	v_cvt_pk_bf16_f32 v214, v170, v140
	v_cvt_pk_bf16_f32 v218, v171, v141
	v_cvt_pk_bf16_f32 v222, v172, v142
	v_cvt_pk_bf16_f32 v226, v173, v143
	v_cvt_pk_bf16_f32 v230, v174, v144
	v_cvt_pk_bf16_f32 v234, v175, v145
	v_cvt_pk_bf16_f32 v238, v176, v146
	v_cvt_pk_bf16_f32 v242, v177, v147
	v_lshlrev_b32_e32 v108, 16, v76
	v_and_b32_e32 v109, 0xffff0000, v76
	v_lshlrev_b32_e32 v110, 16, v77
	v_and_b32_e32 v111, 0xffff0000, v77
	v_lshlrev_b32_e32 v112, 16, v78
	v_and_b32_e32 v113, 0xffff0000, v78
	v_lshlrev_b32_e32 v114, 16, v79
	v_and_b32_e32 v115, 0xffff0000, v79
	v_pk_mul_f32 v[132:133], v[116:117], v[16:17]
	v_pk_fma_f32 v[132:133], v[124:125], v[24:25], v[132:133]
	v_pk_fma_f32 v[132:133], v[100:101], v[32:33], v[132:133]
	v_pk_fma_f32 v[132:133], v[108:109], v[40:41], v[132:133]
	v_pk_add_f32 v[132:133], v[132:133], v[48:49]
	v_pk_mul_f32 v[134:135], v[118:119], v[18:19]
	v_pk_fma_f32 v[134:135], v[126:127], v[26:27], v[134:135]
	v_pk_fma_f32 v[134:135], v[102:103], v[34:35], v[134:135]
	v_pk_fma_f32 v[134:135], v[110:111], v[42:43], v[134:135]
	v_pk_add_f32 v[134:135], v[134:135], v[50:51]
	v_pk_mul_f32 v[136:137], v[120:121], v[20:21]
	v_pk_fma_f32 v[136:137], v[128:129], v[28:29], v[136:137]
	v_pk_fma_f32 v[136:137], v[104:105], v[36:37], v[136:137]
	v_pk_fma_f32 v[136:137], v[112:113], v[44:45], v[136:137]
	v_pk_add_f32 v[136:137], v[136:137], v[52:53]
	v_pk_mul_f32 v[138:139], v[122:123], v[22:23]
	v_pk_fma_f32 v[138:139], v[130:131], v[30:31], v[138:139]
	v_pk_fma_f32 v[138:139], v[106:107], v[38:39], v[138:139]
	v_pk_fma_f32 v[138:139], v[114:115], v[46:47], v[138:139]
	v_pk_add_f32 v[138:139], v[138:139], v[54:55]
	v_pk_mul_f32 v[140:141], v[132:133], v[12:13] op_sel:[0,0] op_sel_hi:[1,0]
	v_pk_mul_f32 v[142:143], v[134:135], v[12:13] op_sel:[0,0] op_sel_hi:[1,0]
	v_pk_mul_f32 v[144:145], v[136:137], v[12:13] op_sel:[0,0] op_sel_hi:[1,0]
	v_pk_mul_f32 v[146:147], v[138:139], v[12:13] op_sel:[0,0] op_sel_hi:[1,0]
	v_exp_f32_e32 v140, v140
	v_exp_f32_e32 v141, v141
	v_exp_f32_e32 v142, v142
	v_exp_f32_e32 v143, v143
	v_exp_f32_e32 v144, v144
	v_exp_f32_e32 v145, v145
	v_exp_f32_e32 v146, v146
	v_exp_f32_e32 v147, v147
	v_pk_add_f32 v[140:141], v[140:141], v[12:13] op_sel:[0,1] op_sel_hi:[1,1]
	v_pk_add_f32 v[142:143], v[142:143], v[12:13] op_sel:[0,1] op_sel_hi:[1,1]
	v_pk_add_f32 v[144:145], v[144:145], v[12:13] op_sel:[0,1] op_sel_hi:[1,1]
	v_pk_add_f32 v[146:147], v[146:147], v[12:13] op_sel:[0,1] op_sel_hi:[1,1]
	v_rcp_f32_e32 v140, v140
	v_rcp_f32_e32 v141, v141
	v_rcp_f32_e32 v142, v142
	v_rcp_f32_e32 v143, v143
	v_rcp_f32_e32 v144, v144
	v_rcp_f32_e32 v145, v145
	v_rcp_f32_e32 v146, v146
	v_rcp_f32_e32 v147, v147
	v_pk_mul_f32 v[140:141], v[132:133], v[140:141]
	v_pk_mul_f32 v[142:143], v[134:135], v[142:143]
	v_pk_mul_f32 v[144:145], v[136:137], v[144:145]
	v_pk_mul_f32 v[146:147], v[138:139], v[146:147]
	v_cvt_pk_bf16_f32 v148, v140, v141
	v_cvt_pk_bf16_f32 v149, v142, v143
	v_cvt_pk_bf16_f32 v150, v144, v145
	v_cvt_pk_bf16_f32 v151, v146, v147
	global_store_dwordx4 v5, v[148:151], s[30:31]
	s_add_u32 s30, s30, 0x1800
	s_addc_u32 s31, s31, 0
	v_mov_b32_e32 v170, v140
	v_mov_b32_e32 v171, v141
	v_mov_b32_e32 v172, v142
	v_mov_b32_e32 v173, v143
	v_mov_b32_e32 v174, v144
	v_mov_b32_e32 v175, v145
	v_mov_b32_e32 v176, v146
	v_mov_b32_e32 v177, v147
	v_lshlrev_b32_e32 v116, 16, v80
	v_and_b32_e32 v117, 0xffff0000, v80
	v_lshlrev_b32_e32 v118, 16, v81
	v_and_b32_e32 v119, 0xffff0000, v81
	v_lshlrev_b32_e32 v120, 16, v82
	v_and_b32_e32 v121, 0xffff0000, v82
	v_lshlrev_b32_e32 v122, 16, v83
	v_and_b32_e32 v123, 0xffff0000, v83
	v_pk_mul_f32 v[132:133], v[124:125], v[16:17]
	v_pk_fma_f32 v[132:133], v[100:101], v[24:25], v[132:133]
	v_pk_fma_f32 v[132:133], v[108:109], v[32:33], v[132:133]
	v_pk_fma_f32 v[132:133], v[116:117], v[40:41], v[132:133]
	v_pk_add_f32 v[132:133], v[132:133], v[48:49]
; __device__ __forceinline__ unsigned pk2(float lo, float hi) { unsigned r; asm("v_cvt_pk_bf16_f32 %0, %1, %2" : "=v"(r) : "v"(lo), "v"(hi)); return r; }
; __device__ __forceinline__ float siluf_(float x) { return x * __builtin_amdgcn_rcpf(1.f + __expf(-x)); }
; __device__ __forceinline__ void ssdconv_prompt_item(const bf16_t* PROJ, int row0, bool has_hist, int cgi, const float* w, const float* bias, bf16_t* XBC, float* state_out,
;                                                     const float* DT, const float* CS, bf16_t* XT1, bf16_t* XT2, bf16_t* BT) {
;     ...
;     for (int t = 0; t < 8; ++t) {
;         float cur[8];
;         unpack8(rows[t], cur);
; #pragma unroll
;         for (int e = 0; e < 8; ++e) { float v = h0[e] * wv[0][e] + h1[e] * wv[1][e] + h2[e] * wv[2][e] + cur[e] * wv[3][e] + bv[e]; o[t][e] = siluf_(v); h0[e] = h1[e]; h1[e] = h2[e]; h2[e] = cur[e]; }
;         *(u32x4*)(XBC + (size_t)(row0 + t) * XBCW + c0) = pack8(o[t]);
;     ...
;     } else if (isb) {
; #pragma unroll
;         for (int e = 0; e < 8; ++e) { u32x4 a;
;             a.x = pk2(o[0][e], o[1][e]); a.y = pk2(o[2][e], o[3][e]); a.z = pk2(o[4][e], o[5][e]); a.w = pk2(o[6][e], o[7][e]);
;             *(u32x4*)(BT + ((size_t)chunk * 512 + (c0 - 2048) + e) * 128 + jb) = a; }
	v_pk_mul_f32 v[134:135], v[126:127], v[18:19]
	v_pk_fma_f32 v[134:135], v[102:103], v[26:27], v[134:135]
	v_pk_fma_f32 v[134:135], v[110:111], v[34:35], v[134:135]
	v_pk_fma_f32 v[134:135], v[118:119], v[42:43], v[134:135]
	v_pk_add_f32 v[134:135], v[134:135], v[50:51]
	v_pk_mul_f32 v[136:137], v[128:129], v[20:21]
	v_pk_fma_f32 v[136:137], v[104:105], v[28:29], v[136:137]
	v_pk_fma_f32 v[136:137], v[112:113], v[36:37], v[136:137]
	v_pk_fma_f32 v[136:137], v[120:121], v[44:45], v[136:137]
	v_pk_add_f32 v[136:137], v[136:137], v[52:53]
	v_pk_mul_f32 v[138:139], v[130:131], v[22:23]
	v_pk_fma_f32 v[138:139], v[106:107], v[30:31], v[138:139]
	v_pk_fma_f32 v[138:139], v[114:115], v[38:39], v[138:139]
	v_pk_fma_f32 v[138:139], v[122:123], v[46:47], v[138:139]
	v_pk_add_f32 v[138:139], v[138:139], v[54:55]
	v_pk_mul_f32 v[140:141], v[132:133], v[12:13] op_sel:[0,0] op_sel_hi:[1,0]
	v_pk_mul_f32 v[142:143], v[134:135], v[12:13] op_sel:[0,0] op_sel_hi:[1,0]
	v_pk_mul_f32 v[144:145], v[136:137], v[12:13] op_sel:[0,0] op_sel_hi:[1,0]
	v_pk_mul_f32 v[146:147], v[138:139], v[12:13] op_sel:[0,0] op_sel_hi:[1,0]
	v_exp_f32_e32 v140, v140
	v_exp_f32_e32 v141, v141
	v_exp_f32_e32 v142, v142
	v_exp_f32_e32 v143, v143
	v_exp_f32_e32 v144, v144
	v_exp_f32_e32 v145, v145
	v_exp_f32_e32 v146, v146
	v_exp_f32_e32 v147, v147
	v_pk_add_f32 v[140:141], v[140:141], v[12:13] op_sel:[0,1] op_sel_hi:[1,1]
	v_pk_add_f32 v[142:143], v[142:143], v[12:13] op_sel:[0,1] op_sel_hi:[1,1]
	v_pk_add_f32 v[144:145], v[144:145], v[12:13] op_sel:[0,1] op_sel_hi:[1,1]
	v_pk_add_f32 v[146:147], v[146:147], v[12:13] op_sel:[0,1] op_sel_hi:[1,1]
	v_rcp_f32_e32 v140, v140
	v_rcp_f32_e32 v141, v141
	v_rcp_f32_e32 v142, v142
	v_rcp_f32_e32 v143, v143
	v_rcp_f32_e32 v144, v144
	v_rcp_f32_e32 v145, v145
	v_rcp_f32_e32 v146, v146
	v_rcp_f32_e32 v147, v147
	v_pk_mul_f32 v[140:141], v[132:133], v[140:141]
	v_pk_mul_f32 v[142:143], v[134:135], v[142:143]
	v_pk_mul_f32 v[144:145], v[136:137], v[144:145]
	v_pk_mul_f32 v[146:147], v[138:139], v[146:147]
	v_cvt_pk_bf16_f32 v148, v140, v141
	v_cvt_pk_bf16_f32 v149, v142, v143
	v_cvt_pk_bf16_f32 v150, v144, v145
	v_cvt_pk_bf16_f32 v151, v146, v147
	global_store_dwordx4 v5, v[148:151], s[30:31]
	s_add_u32 s30, s30, 0x1800
	s_addc_u32 s31, s31, 0
	v_cvt_pk_bf16_f32 v215, v170, v140
	v_cvt_pk_bf16_f32 v219, v171, v141
	v_cvt_pk_bf16_f32 v223, v172, v142
	v_cvt_pk_bf16_f32 v227, v173, v143
	v_cvt_pk_bf16_f32 v231, v174, v144
	v_cvt_pk_bf16_f32 v235, v175, v145
	v_cvt_pk_bf16_f32 v239, v176, v146
	v_cvt_pk_bf16_f32 v243, v177, v147
	v_lshlrev_b32_e32 v124, 16, v84
	v_and_b32_e32 v125, 0xffff0000, v84
	v_lshlrev_b32_e32 v126, 16, v85
	v_and_b32_e32 v127, 0xffff0000, v85
	v_lshlrev_b32_e32 v128, 16, v86
	v_and_b32_e32 v129, 0xffff0000, v86
	v_lshlrev_b32_e32 v130, 16, v87
	v_and_b32_e32 v131, 0xffff0000, v87
	v_pk_mul_f32 v[132:133], v[100:101], v[16:17]
	v_pk_fma_f32 v[132:133], v[108:109], v[24:25], v[132:133]
	v_pk_fma_f32 v[132:133], v[116:117], v[32:33], v[132:133]
	v_pk_fma_f32 v[132:133], v[124:125], v[40:41], v[132:133]
	v_pk_add_f32 v[132:133], v[132:133], v[48:49]
	v_pk_mul_f32 v[134:135], v[102:103], v[18:19]
	v_pk_fma_f32 v[134:135], v[110:111], v[26:27], v[134:135]
	v_pk_fma_f32 v[134:135], v[118:119], v[34:35], v[134:135]
	v_pk_fma_f32 v[134:135], v[126:127], v[42:43], v[134:135]
	v_pk_add_f32 v[134:135], v[134:135], v[50:51]
	v_pk_mul_f32 v[136:137], v[104:105], v[20:21]
	v_pk_fma_f32 v[136:137], v[112:113], v[28:29], v[136:137]
	v_pk_fma_f32 v[136:137], v[120:121], v[36:37], v[136:137]
	v_pk_fma_f32 v[136:137], v[128:129], v[44:45], v[136:137]
	v_pk_add_f32 v[136:137], v[136:137], v[52:53]
	v_pk_mul_f32 v[138:139], v[106:107], v[22:23]
	v_pk_fma_f32 v[138:139], v[114:115], v[30:31], v[138:139]
	v_pk_fma_f32 v[138:139], v[122:123], v[38:39], v[138:139]
	v_pk_fma_f32 v[138:139], v[130:131], v[46:47], v[138:139]
	v_pk_add_f32 v[138:139], v[138:139], v[54:55]
	v_pk_mul_f32 v[140:141], v[132:133], v[12:13] op_sel:[0,0] op_sel_hi:[1,0]
	v_pk_mul_f32 v[142:143], v[134:135], v[12:13] op_sel:[0,0] op_sel_hi:[1,0]
	v_pk_mul_f32 v[144:145], v[136:137], v[12:13] op_sel:[0,0] op_sel_hi:[1,0]
	v_pk_mul_f32 v[146:147], v[138:139], v[12:13] op_sel:[0,0] op_sel_hi:[1,0]
	v_exp_f32_e32 v140, v140
	v_exp_f32_e32 v141, v141
	v_exp_f32_e32 v142, v142
	v_exp_f32_e32 v143, v143
	v_exp_f32_e32 v144, v144
	v_exp_f32_e32 v145, v145
	v_exp_f32_e32 v146, v146
	v_exp_f32_e32 v147, v147
	v_pk_add_f32 v[140:141], v[140:141], v[12:13] op_sel:[0,1] op_sel_hi:[1,1]
	v_pk_add_f32 v[142:143], v[142:143], v[12:13] op_sel:[0,1] op_sel_hi:[1,1]
	v_pk_add_f32 v[144:145], v[144:145], v[12:13] op_sel:[0,1] op_sel_hi:[1,1]
	v_pk_add_f32 v[146:147], v[146:147], v[12:13] op_sel:[0,1] op_sel_hi:[1,1]
	v_rcp_f32_e32 v140, v140
	v_rcp_f32_e32 v141, v141
	v_rcp_f32_e32 v142, v142
	v_rcp_f32_e32 v143, v143
	v_rcp_f32_e32 v144, v144
	v_rcp_f32_e32 v145, v145
	v_rcp_f32_e32 v146, v146
	v_rcp_f32_e32 v147, v147
	v_pk_mul_f32 v[140:141], v[132:133], v[140:141]
	v_pk_mul_f32 v[142:143], v[134:135], v[142:143]
	v_pk_mul_f32 v[144:145], v[136:137], v[144:145]
	v_pk_mul_f32 v[146:147], v[138:139], v[146:147]
	v_cvt_pk_bf16_f32 v148, v140, v141
	v_cvt_pk_bf16_f32 v149, v142, v143
	v_cvt_pk_bf16_f32 v150, v144, v145
	v_cvt_pk_bf16_f32 v151, v146, v147
	global_store_dwordx4 v5, v[148:151], s[30:31]
	s_add_u32 s30, s30, 0x1800
	s_addc_u32 s31, s31, 0
	v_mov_b32_e32 v170, v140
	v_mov_b32_e32 v171, v141
	v_mov_b32_e32 v172, v142
	v_mov_b32_e32 v173, v143
	v_mov_b32_e32 v174, v144
	v_mov_b32_e32 v175, v145
	v_mov_b32_e32 v176, v146
	v_mov_b32_e32 v177, v147
	v_lshlrev_b32_e32 v100, 16, v88
; __device__ __forceinline__ unsigned pk2(float lo, float hi) { unsigned r; asm("v_cvt_pk_bf16_f32 %0, %1, %2" : "=v"(r) : "v"(lo), "v"(hi)); return r; }
; __device__ __forceinline__ float siluf_(float x) { return x * __builtin_amdgcn_rcpf(1.f + __expf(-x)); }
; __device__ __forceinline__ void ssdconv_prompt_item(const bf16_t* PROJ, int row0, bool has_hist, int cgi, const float* w, const float* bias, bf16_t* XBC, float* state_out,
;                                                     const float* DT, const float* CS, bf16_t* XT1, bf16_t* XT2, bf16_t* BT) {
;     ...
;     for (int t = 0; t < 8; ++t) {
;         float cur[8];
;         unpack8(rows[t], cur);
; #pragma unroll
;         for (int e = 0; e < 8; ++e) { float v = h0[e] * wv[0][e] + h1[e] * wv[1][e] + h2[e] * wv[2][e] + cur[e] * wv[3][e] + bv[e]; o[t][e] = siluf_(v); h0[e] = h1[e]; h1[e] = h2[e]; h2[e] = cur[e]; }
;         *(u32x4*)(XBC + (size_t)(row0 + t) * XBCW + c0) = pack8(o[t]);
;     ...
;     } else if (isb) {
; #pragma unroll
;         for (int e = 0; e < 8; ++e) { u32x4 a;
;             a.x = pk2(o[0][e], o[1][e]); a.y = pk2(o[2][e], o[3][e]); a.z = pk2(o[4][e], o[5][e]); a.w = pk2(o[6][e], o[7][e]);
;             *(u32x4*)(BT + ((size_t)chunk * 512 + (c0 - 2048) + e) * 128 + jb) = a; }
	v_and_b32_e32 v101, 0xffff0000, v88
	v_lshlrev_b32_e32 v102, 16, v89
	v_and_b32_e32 v103, 0xffff0000, v89
	v_lshlrev_b32_e32 v104, 16, v90
	v_and_b32_e32 v105, 0xffff0000, v90
	v_lshlrev_b32_e32 v106, 16, v91
	v_and_b32_e32 v107, 0xffff0000, v91
	v_pk_mul_f32 v[132:133], v[108:109], v[16:17]
	v_pk_fma_f32 v[132:133], v[116:117], v[24:25], v[132:133]
	v_pk_fma_f32 v[132:133], v[124:125], v[32:33], v[132:133]
	v_pk_fma_f32 v[132:133], v[100:101], v[40:41], v[132:133]
	v_pk_add_f32 v[132:133], v[132:133], v[48:49]
	v_pk_mul_f32 v[134:135], v[110:111], v[18:19]
	v_pk_fma_f32 v[134:135], v[118:119], v[26:27], v[134:135]
	v_pk_fma_f32 v[134:135], v[126:127], v[34:35], v[134:135]
	v_pk_fma_f32 v[134:135], v[102:103], v[42:43], v[134:135]
	v_pk_add_f32 v[134:135], v[134:135], v[50:51]
	v_pk_mul_f32 v[136:137], v[112:113], v[20:21]
	v_pk_fma_f32 v[136:137], v[120:121], v[28:29], v[136:137]
	v_pk_fma_f32 v[136:137], v[128:129], v[36:37], v[136:137]
	v_pk_fma_f32 v[136:137], v[104:105], v[44:45], v[136:137]
	v_pk_add_f32 v[136:137], v[136:137], v[52:53]
	v_pk_mul_f32 v[138:139], v[114:115], v[22:23]
	v_pk_fma_f32 v[138:139], v[122:123], v[30:31], v[138:139]
	v_pk_fma_f32 v[138:139], v[130:131], v[38:39], v[138:139]
	v_pk_fma_f32 v[138:139], v[106:107], v[46:47], v[138:139]
	v_pk_add_f32 v[138:139], v[138:139], v[54:55]
	v_pk_mul_f32 v[140:141], v[132:133], v[12:13] op_sel:[0,0] op_sel_hi:[1,0]
	v_pk_mul_f32 v[142:143], v[134:135], v[12:13] op_sel:[0,0] op_sel_hi:[1,0]
	v_pk_mul_f32 v[144:145], v[136:137], v[12:13] op_sel:[0,0] op_sel_hi:[1,0]
	v_pk_mul_f32 v[146:147], v[138:139], v[12:13] op_sel:[0,0] op_sel_hi:[1,0]
	v_exp_f32_e32 v140, v140
	v_exp_f32_e32 v141, v141
	v_exp_f32_e32 v142, v142
	v_exp_f32_e32 v143, v143
	v_exp_f32_e32 v144, v144
	v_exp_f32_e32 v145, v145
	v_exp_f32_e32 v146, v146
	v_exp_f32_e32 v147, v147
	v_pk_add_f32 v[140:141], v[140:141], v[12:13] op_sel:[0,1] op_sel_hi:[1,1]
	v_pk_add_f32 v[142:143], v[142:143], v[12:13] op_sel:[0,1] op_sel_hi:[1,1]
	v_pk_add_f32 v[144:145], v[144:145], v[12:13] op_sel:[0,1] op_sel_hi:[1,1]
	v_pk_add_f32 v[146:147], v[146:147], v[12:13] op_sel:[0,1] op_sel_hi:[1,1]
	v_rcp_f32_e32 v140, v140
	v_rcp_f32_e32 v141, v141
	v_rcp_f32_e32 v142, v142
	v_rcp_f32_e32 v143, v143
	v_rcp_f32_e32 v144, v144
	v_rcp_f32_e32 v145, v145
	v_rcp_f32_e32 v146, v146
	v_rcp_f32_e32 v147, v147
	v_pk_mul_f32 v[140:141], v[132:133], v[140:141]
	v_pk_mul_f32 v[142:143], v[134:135], v[142:143]
	v_pk_mul_f32 v[144:145], v[136:137], v[144:145]
	v_pk_mul_f32 v[146:147], v[138:139], v[146:147]
	v_cvt_pk_bf16_f32 v148, v140, v141
	v_cvt_pk_bf16_f32 v149, v142, v143
	v_cvt_pk_bf16_f32 v150, v144, v145
	v_cvt_pk_bf16_f32 v151, v146, v147
	global_store_dwordx4 v5, v[148:151], s[30:31]
	s_add_u32 s30, s30, 0x1800
	s_addc_u32 s31, s31, 0
	v_cvt_pk_bf16_f32 v216, v170, v140
	v_cvt_pk_bf16_f32 v220, v171, v141
	v_cvt_pk_bf16_f32 v224, v172, v142
	v_cvt_pk_bf16_f32 v228, v173, v143
	v_cvt_pk_bf16_f32 v232, v174, v144
	v_cvt_pk_bf16_f32 v236, v175, v145
	v_cvt_pk_bf16_f32 v240, v176, v146
	v_cvt_pk_bf16_f32 v244, v177, v147
	v_lshlrev_b32_e32 v108, 16, v92
	v_and_b32_e32 v109, 0xffff0000, v92
	v_lshlrev_b32_e32 v110, 16, v93
	v_and_b32_e32 v111, 0xffff0000, v93
	v_lshlrev_b32_e32 v112, 16, v94
	v_and_b32_e32 v113, 0xffff0000, v94
	v_lshlrev_b32_e32 v114, 16, v95
	v_and_b32_e32 v115, 0xffff0000, v95
	v_pk_mul_f32 v[132:133], v[116:117], v[16:17]
	v_pk_fma_f32 v[132:133], v[124:125], v[24:25], v[132:133]
	v_pk_fma_f32 v[132:133], v[100:101], v[32:33], v[132:133]
	v_pk_fma_f32 v[132:133], v[108:109], v[40:41], v[132:133]
	v_pk_add_f32 v[132:133], v[132:133], v[48:49]
	v_pk_mul_f32 v[134:135], v[118:119], v[18:19]
	v_pk_fma_f32 v[134:135], v[126:127], v[26:27], v[134:135]
	v_pk_fma_f32 v[134:135], v[102:103], v[34:35], v[134:135]
	v_pk_fma_f32 v[134:135], v[110:111], v[42:43], v[134:135]
	v_pk_add_f32 v[134:135], v[134:135], v[50:51]
	v_pk_mul_f32 v[136:137], v[120:121], v[20:21]
	v_pk_fma_f32 v[136:137], v[128:129], v[28:29], v[136:137]
	v_pk_fma_f32 v[136:137], v[104:105], v[36:37], v[136:137]
	v_pk_fma_f32 v[136:137], v[112:113], v[44:45], v[136:137]
	v_pk_add_f32 v[136:137], v[136:137], v[52:53]
	v_pk_mul_f32 v[138:139], v[122:123], v[22:23]
	v_pk_fma_f32 v[138:139], v[130:131], v[30:31], v[138:139]
	v_pk_fma_f32 v[138:139], v[106:107], v[38:39], v[138:139]
	v_pk_fma_f32 v[138:139], v[114:115], v[46:47], v[138:139]
	v_pk_add_f32 v[138:139], v[138:139], v[54:55]
	v_pk_mul_f32 v[140:141], v[132:133], v[12:13] op_sel:[0,0] op_sel_hi:[1,0]
	v_pk_mul_f32 v[142:143], v[134:135], v[12:13] op_sel:[0,0] op_sel_hi:[1,0]
	v_pk_mul_f32 v[144:145], v[136:137], v[12:13] op_sel:[0,0] op_sel_hi:[1,0]
	v_pk_mul_f32 v[146:147], v[138:139], v[12:13] op_sel:[0,0] op_sel_hi:[1,0]
	v_exp_f32_e32 v140, v140
	v_exp_f32_e32 v141, v141
	v_exp_f32_e32 v142, v142
	v_exp_f32_e32 v143, v143
	v_exp_f32_e32 v144, v144
	v_exp_f32_e32 v145, v145
	v_exp_f32_e32 v146, v146
	v_exp_f32_e32 v147, v147
	v_pk_add_f32 v[140:141], v[140:141], v[12:13] op_sel:[0,1] op_sel_hi:[1,1]
	v_pk_add_f32 v[142:143], v[142:143], v[12:13] op_sel:[0,1] op_sel_hi:[1,1]
; __device__ __forceinline__ unsigned pk2(float lo, float hi) { unsigned r; asm("v_cvt_pk_bf16_f32 %0, %1, %2" : "=v"(r) : "v"(lo), "v"(hi)); return r; }
; __device__ __forceinline__ void ssdconv_prompt_item(const bf16_t* PROJ, int row0, bool has_hist, int cgi, const float* w, const float* bias, bf16_t* XBC, float* state_out,
;                                                     const float* DT, const float* CS, bf16_t* XT1, bf16_t* XT2, bf16_t* BT) {
;     ...
;     if (state_out) {
;         *(f32x4*)(state_out + 0 * XBCW + c0) = (f32x4){h0[0], h0[1], h0[2], h0[3]}; *(f32x4*)(state_out + 0 * XBCW + c0 + 4) = (f32x4){h0[4], h0[5], h0[6], h0[7]};
;         *(f32x4*)(state_out + 1 * XBCW + c0) = (f32x4){h1[0], h1[1], h1[2], h1[3]}; *(f32x4*)(state_out + 1 * XBCW + c0 + 4) = (f32x4){h1[4], h1[5], h1[6], h1[7]};
;         *(f32x4*)(state_out + 2 * XBCW + c0) = (f32x4){h2[0], h2[1], h2[2], h2[3]}; *(f32x4*)(state_out + 2 * XBCW + c0 + 4) = (f32x4){h2[4], h2[5], h2[6], h2[7]};
;     ...
;     } else if (isb) {
; #pragma unroll
;         for (int e = 0; e < 8; ++e) { u32x4 a;
;             a.x = pk2(o[0][e], o[1][e]); a.y = pk2(o[2][e], o[3][e]); a.z = pk2(o[4][e], o[5][e]); a.w = pk2(o[6][e], o[7][e]);
;             *(u32x4*)(BT + ((size_t)chunk * 512 + (c0 - 2048) + e) * 128 + jb) = a; }
	v_pk_add_f32 v[144:145], v[144:145], v[12:13] op_sel:[0,1] op_sel_hi:[1,1]
	v_pk_add_f32 v[146:147], v[146:147], v[12:13] op_sel:[0,1] op_sel_hi:[1,1]
	v_rcp_f32_e32 v140, v140
	v_rcp_f32_e32 v141, v141
	v_rcp_f32_e32 v142, v142
	v_rcp_f32_e32 v143, v143
	v_rcp_f32_e32 v144, v144
	v_rcp_f32_e32 v145, v145
	v_rcp_f32_e32 v146, v146
	v_rcp_f32_e32 v147, v147
	v_pk_mul_f32 v[140:141], v[132:133], v[140:141]
	v_pk_mul_f32 v[142:143], v[134:135], v[142:143]
	v_pk_mul_f32 v[144:145], v[136:137], v[144:145]
	v_pk_mul_f32 v[146:147], v[138:139], v[146:147]
	v_cvt_pk_bf16_f32 v148, v140, v141
	v_cvt_pk_bf16_f32 v149, v142, v143
	v_cvt_pk_bf16_f32 v150, v144, v145
	v_cvt_pk_bf16_f32 v151, v146, v147
	global_store_dwordx4 v5, v[148:151], s[30:31]
	s_add_u32 s30, s30, 0x1800
	s_addc_u32 s31, s31, 0
	v_mov_b32_e32 v170, v140
	v_mov_b32_e32 v171, v141
	v_mov_b32_e32 v172, v142
	v_mov_b32_e32 v173, v143
	v_mov_b32_e32 v174, v144
	v_mov_b32_e32 v175, v145
	v_mov_b32_e32 v176, v146
	v_mov_b32_e32 v177, v147
	v_lshlrev_b32_e32 v116, 16, v96
	v_and_b32_e32 v117, 0xffff0000, v96
	v_lshlrev_b32_e32 v118, 16, v97
	v_and_b32_e32 v119, 0xffff0000, v97
	v_lshlrev_b32_e32 v120, 16, v98
	v_and_b32_e32 v121, 0xffff0000, v98
	v_lshlrev_b32_e32 v122, 16, v99
	v_and_b32_e32 v123, 0xffff0000, v99
	v_pk_mul_f32 v[132:133], v[124:125], v[16:17]
	v_pk_fma_f32 v[132:133], v[100:101], v[24:25], v[132:133]
	v_pk_fma_f32 v[132:133], v[108:109], v[32:33], v[132:133]
	v_pk_fma_f32 v[132:133], v[116:117], v[40:41], v[132:133]
	v_pk_add_f32 v[132:133], v[132:133], v[48:49]
	v_pk_mul_f32 v[134:135], v[126:127], v[18:19]
	v_pk_fma_f32 v[134:135], v[102:103], v[26:27], v[134:135]
	v_pk_fma_f32 v[134:135], v[110:111], v[34:35], v[134:135]
	v_pk_fma_f32 v[134:135], v[118:119], v[42:43], v[134:135]
	v_pk_add_f32 v[134:135], v[134:135], v[50:51]
	v_pk_mul_f32 v[136:137], v[128:129], v[20:21]
	v_pk_fma_f32 v[136:137], v[104:105], v[28:29], v[136:137]
	v_pk_fma_f32 v[136:137], v[112:113], v[36:37], v[136:137]
	v_pk_fma_f32 v[136:137], v[120:121], v[44:45], v[136:137]
	v_pk_add_f32 v[136:137], v[136:137], v[52:53]
	v_pk_mul_f32 v[138:139], v[130:131], v[22:23]
	v_pk_fma_f32 v[138:139], v[106:107], v[30:31], v[138:139]
	v_pk_fma_f32 v[138:139], v[114:115], v[38:39], v[138:139]
	v_pk_fma_f32 v[138:139], v[122:123], v[46:47], v[138:139]
	v_pk_add_f32 v[138:139], v[138:139], v[54:55]
	v_pk_mul_f32 v[140:141], v[132:133], v[12:13] op_sel:[0,0] op_sel_hi:[1,0]
	v_pk_mul_f32 v[142:143], v[134:135], v[12:13] op_sel:[0,0] op_sel_hi:[1,0]
	v_pk_mul_f32 v[144:145], v[136:137], v[12:13] op_sel:[0,0] op_sel_hi:[1,0]
	v_pk_mul_f32 v[146:147], v[138:139], v[12:13] op_sel:[0,0] op_sel_hi:[1,0]
	v_exp_f32_e32 v140, v140
	v_exp_f32_e32 v141, v141
	v_exp_f32_e32 v142, v142
	v_exp_f32_e32 v143, v143
	v_exp_f32_e32 v144, v144
	v_exp_f32_e32 v145, v145
	v_exp_f32_e32 v146, v146
	v_exp_f32_e32 v147, v147
	v_pk_add_f32 v[140:141], v[140:141], v[12:13] op_sel:[0,1] op_sel_hi:[1,1]
	v_pk_add_f32 v[142:143], v[142:143], v[12:13] op_sel:[0,1] op_sel_hi:[1,1]
	v_pk_add_f32 v[144:145], v[144:145], v[12:13] op_sel:[0,1] op_sel_hi:[1,1]
	v_pk_add_f32 v[146:147], v[146:147], v[12:13] op_sel:[0,1] op_sel_hi:[1,1]
	v_rcp_f32_e32 v140, v140
	v_rcp_f32_e32 v141, v141
	v_rcp_f32_e32 v142, v142
	v_rcp_f32_e32 v143, v143
	v_rcp_f32_e32 v144, v144
	v_rcp_f32_e32 v145, v145
	v_rcp_f32_e32 v146, v146
	v_rcp_f32_e32 v147, v147
	v_pk_mul_f32 v[140:141], v[132:133], v[140:141]
	v_pk_mul_f32 v[142:143], v[134:135], v[142:143]
	v_pk_mul_f32 v[144:145], v[136:137], v[144:145]
	v_pk_mul_f32 v[146:147], v[138:139], v[146:147]
	v_cvt_pk_bf16_f32 v148, v140, v141
	v_cvt_pk_bf16_f32 v149, v142, v143
	v_cvt_pk_bf16_f32 v150, v144, v145
	v_cvt_pk_bf16_f32 v151, v146, v147
	global_store_dwordx4 v5, v[148:151], s[30:31]
	v_cvt_pk_bf16_f32 v217, v170, v140
	v_cvt_pk_bf16_f32 v221, v171, v141
	v_cvt_pk_bf16_f32 v225, v172, v142
	v_cvt_pk_bf16_f32 v229, v173, v143
	v_cvt_pk_bf16_f32 v233, v174, v144
	v_cvt_pk_bf16_f32 v237, v175, v145
	v_cvt_pk_bf16_f32 v241, v176, v146
	v_cvt_pk_bf16_f32 v245, v177, v147
	global_store_dwordx4 v9, v[214:217], s[34:35] offset:0
	global_store_dwordx4 v9, v[218:221], s[34:35] offset:256
	global_store_dwordx4 v9, v[222:225], s[34:35] offset:512
	global_store_dwordx4 v9, v[226:229], s[34:35] offset:768
	global_store_dwordx4 v9, v[230:233], s[34:35] offset:1024
	global_store_dwordx4 v9, v[234:237], s[34:35] offset:1280
	global_store_dwordx4 v9, v[238:241], s[34:35] offset:1536
	global_store_dwordx4 v9, v[242:245], s[34:35] offset:1792
	s_and_b32 s33, s5, 31
	s_cmp_eq_u32 s33, 31
	s_cbranch_scc0 .Lp2b_nostate_b
	s_mov_b64 s[48:49], exec
	s_and_b64 exec, exec, s[46:47]
	global_store_dwordx4 v11, v[100:103], s[38:39]
	global_store_dwordx4 v11, v[104:107], s[38:39] offset:16
	s_add_u32 s38, s38, 0x3000
	s_addc_u32 s39, s39, 0
	global_store_dwordx4 v11, v[108:111], s[38:39]
	global_store_dwordx4 v11, v[112:115], s[38:39] offset:16
	s_add_u32 s38, s38, 0x3000
	s_addc_u32 s39, s39, 0
	global_store_dwordx4 v11, v[116:119], s[38:39]
	global_store_dwordx4 v11, v[120:123], s[38:39] offset:16
	s_mov_b64 exec, s[48:49]

; __device__ __forceinline__ float siluf_(float x) { return x * __builtin_amdgcn_rcpf(1.f + __expf(-x)); }
; __device__ __forceinline__ void ssdconv_prompt_item(const bf16_t* PROJ, int row0, bool has_hist, int cgi, const float* w, const float* bias, bf16_t* XBC, float* state_out,
;                                                     const float* DT, const float* CS, bf16_t* XT1, bf16_t* XT2, bf16_t* BT) {
;     ...
;     for (int t = 0; t < 8; ++t) {
;         float cur[8];
;         unpack8(rows[t], cur);
; #pragma unroll
;         for (int e = 0; e < 8; ++e) { float v = h0[e] * wv[0][e] + h1[e] * wv[1][e] + h2[e] * wv[2][e] + cur[e] * wv[3][e] + bv[e]; o[t][e] = siluf_(v); h0[e] = h1[e]; h1[e] = h2[e]; h2[e] = cur[e]; }
;         *(u32x4*)(XBC + (size_t)(row0 + t) * XBCW + c0) = pack8(o[t]);
.Lp2b_c:
	s_waitcnt vmcnt(0)
	v_cndmask_b32_e64 v56, 0, v56, s[44:45]
	v_cndmask_b32_e64 v57, 0, v57, s[44:45]
	v_cndmask_b32_e64 v58, 0, v58, s[44:45]
	v_cndmask_b32_e64 v59, 0, v59, s[44:45]
	v_cndmask_b32_e64 v60, 0, v60, s[44:45]
	v_cndmask_b32_e64 v61, 0, v61, s[44:45]
	v_cndmask_b32_e64 v62, 0, v62, s[44:45]
	v_cndmask_b32_e64 v63, 0, v63, s[44:45]
	v_cndmask_b32_e64 v64, 0, v64, s[44:45]
	v_cndmask_b32_e64 v65, 0, v65, s[44:45]
	v_cndmask_b32_e64 v66, 0, v66, s[44:45]
	v_cndmask_b32_e64 v67, 0, v67, s[44:45]
	v_lshlrev_b32_e32 v100, 16, v56
	v_and_b32_e32 v101, 0xffff0000, v56
	v_lshlrev_b32_e32 v102, 16, v57
	v_and_b32_e32 v103, 0xffff0000, v57
	v_lshlrev_b32_e32 v104, 16, v58
	v_and_b32_e32 v105, 0xffff0000, v58
	v_lshlrev_b32_e32 v106, 16, v59
	v_and_b32_e32 v107, 0xffff0000, v59
	v_lshlrev_b32_e32 v108, 16, v60
	v_and_b32_e32 v109, 0xffff0000, v60
	v_lshlrev_b32_e32 v110, 16, v61
	v_and_b32_e32 v111, 0xffff0000, v61
	v_lshlrev_b32_e32 v112, 16, v62
	v_and_b32_e32 v113, 0xffff0000, v62
	v_lshlrev_b32_e32 v114, 16, v63
	v_and_b32_e32 v115, 0xffff0000, v63
	v_lshlrev_b32_e32 v116, 16, v64
	v_and_b32_e32 v117, 0xffff0000, v64
	v_lshlrev_b32_e32 v118, 16, v65
	v_and_b32_e32 v119, 0xffff0000, v65
	v_lshlrev_b32_e32 v120, 16, v66
	v_and_b32_e32 v121, 0xffff0000, v66
	v_lshlrev_b32_e32 v122, 16, v67
	v_and_b32_e32 v123, 0xffff0000, v67
	v_lshlrev_b32_e32 v124, 16, v68
	v_and_b32_e32 v125, 0xffff0000, v68
	v_lshlrev_b32_e32 v126, 16, v69
	v_and_b32_e32 v127, 0xffff0000, v69
	v_lshlrev_b32_e32 v128, 16, v70
	v_and_b32_e32 v129, 0xffff0000, v70
	v_lshlrev_b32_e32 v130, 16, v71
	v_and_b32_e32 v131, 0xffff0000, v71
	v_pk_mul_f32 v[132:133], v[100:101], v[16:17]
	v_pk_fma_f32 v[132:133], v[108:109], v[24:25], v[132:133]
	v_pk_fma_f32 v[132:133], v[116:117], v[32:33], v[132:133]
	v_pk_fma_f32 v[132:133], v[124:125], v[40:41], v[132:133]
	v_pk_add_f32 v[132:133], v[132:133], v[48:49]
	v_pk_mul_f32 v[134:135], v[102:103], v[18:19]
	v_pk_fma_f32 v[134:135], v[110:111], v[26:27], v[134:135]
	v_pk_fma_f32 v[134:135], v[118:119], v[34:35], v[134:135]
	v_pk_fma_f32 v[134:135], v[126:127], v[42:43], v[134:135]
	v_pk_add_f32 v[134:135], v[134:135], v[50:51]
	v_pk_mul_f32 v[136:137], v[104:105], v[20:21]
	v_pk_fma_f32 v[136:137], v[112:113], v[28:29], v[136:137]
	v_pk_fma_f32 v[136:137], v[120:121], v[36:37], v[136:137]
	v_pk_fma_f32 v[136:137], v[128:129], v[44:45], v[136:137]
	v_pk_add_f32 v[136:137], v[136:137], v[52:53]
	v_pk_mul_f32 v[138:139], v[106:107], v[22:23]
	v_pk_fma_f32 v[138:139], v[114:115], v[30:31], v[138:139]
	v_pk_fma_f32 v[138:139], v[122:123], v[38:39], v[138:139]
	v_pk_fma_f32 v[138:139], v[130:131], v[46:47], v[138:139]
	v_pk_add_f32 v[138:139], v[138:139], v[54:55]
	v_pk_mul_f32 v[140:141], v[132:133], v[12:13] op_sel:[0,0] op_sel_hi:[1,0]
	v_pk_mul_f32 v[142:143], v[134:135], v[12:13] op_sel:[0,0] op_sel_hi:[1,0]
	v_pk_mul_f32 v[144:145], v[136:137], v[12:13] op_sel:[0,0] op_sel_hi:[1,0]
	v_pk_mul_f32 v[146:147], v[138:139], v[12:13] op_sel:[0,0] op_sel_hi:[1,0]
	v_exp_f32_e32 v140, v140
	v_exp_f32_e32 v141, v141
	v_exp_f32_e32 v142, v142
	v_exp_f32_e32 v143, v143
	v_exp_f32_e32 v144, v144
	v_exp_f32_e32 v145, v145
	v_exp_f32_e32 v146, v146
	v_exp_f32_e32 v147, v147
	v_pk_add_f32 v[140:141], v[140:141], v[12:13] op_sel:[0,1] op_sel_hi:[1,1]
	v_pk_add_f32 v[142:143], v[142:143], v[12:13] op_sel:[0,1] op_sel_hi:[1,1]
	v_pk_add_f32 v[144:145], v[144:145], v[12:13] op_sel:[0,1] op_sel_hi:[1,1]
	v_pk_add_f32 v[146:147], v[146:147], v[12:13] op_sel:[0,1] op_sel_hi:[1,1]
	v_rcp_f32_e32 v140, v140
	v_rcp_f32_e32 v141, v141
	v_rcp_f32_e32 v142, v142
	v_rcp_f32_e32 v143, v143
	v_rcp_f32_e32 v144, v144
	v_rcp_f32_e32 v145, v145
	v_rcp_f32_e32 v146, v146
	v_rcp_f32_e32 v147, v147
	v_pk_mul_f32 v[140:141], v[132:133], v[140:141]
	v_pk_mul_f32 v[142:143], v[134:135], v[142:143]
	v_pk_mul_f32 v[144:145], v[136:137], v[144:145]
	v_pk_mul_f32 v[146:147], v[138:139], v[146:147]
	v_cvt_pk_bf16_f32 v148, v140, v141
	v_cvt_pk_bf16_f32 v149, v142, v143
	v_cvt_pk_bf16_f32 v150, v144, v145
	v_cvt_pk_bf16_f32 v151, v146, v147
	global_store_dwordx4 v5, v[148:151], s[30:31]
	s_add_u32 s30, s30, 0x1800
	s_addc_u32 s31, s31, 0
	v_lshlrev_b32_e32 v100, 16, v72
	v_and_b32_e32 v101, 0xffff0000, v72
	v_lshlrev_b32_e32 v102, 16, v73
	v_and_b32_e32 v103, 0xffff0000, v73
	v_lshlrev_b32_e32 v104, 16, v74
	v_and_b32_e32 v105, 0xffff0000, v74
	v_lshlrev_b32_e32 v106, 16, v75
	v_and_b32_e32 v107, 0xffff0000, v75
	v_pk_mul_f32 v[132:133], v[108:109], v[16:17]
	v_pk_fma_f32 v[132:133], v[116:117], v[24:25], v[132:133]
	v_pk_fma_f32 v[132:133], v[124:125], v[32:33], v[132:133]
	v_pk_fma_f32 v[132:133], v[100:101], v[40:41], v[132:133]
	v_pk_add_f32 v[132:133], v[132:133], v[48:49]
	v_pk_mul_f32 v[134:135], v[110:111], v[18:19]
	v_pk_fma_f32 v[134:135], v[118:119], v[26:27], v[134:135]
	v_pk_fma_f32 v[134:135], v[126:127], v[34:35], v[134:135]
	v_pk_fma_f32 v[134:135], v[102:103], v[42:43], v[134:135]
	v_pk_add_f32 v[134:135], v[134:135], v[50:51]
	v_pk_mul_f32 v[136:137], v[112:113], v[20:21]
	v_pk_fma_f32 v[136:137], v[120:121], v[28:29], v[136:137]
	v_pk_fma_f32 v[136:137], v[128:129], v[36:37], v[136:137]
	v_pk_fma_f32 v[136:137], v[104:105], v[44:45], v[136:137]
	v_pk_add_f32 v[136:137], v[136:137], v[52:53]
	v_pk_mul_f32 v[138:139], v[114:115], v[22:23]
	v_pk_fma_f32 v[138:139], v[122:123], v[30:31], v[138:139]
	v_pk_fma_f32 v[138:139], v[130:131], v[38:39], v[138:139]
	v_pk_fma_f32 v[138:139], v[106:107], v[46:47], v[138:139]
	v_pk_add_f32 v[138:139], v[138:139], v[54:55]
	v_pk_mul_f32 v[140:141], v[132:133], v[12:13] op_sel:[0,0] op_sel_hi:[1,0]
; __device__ __forceinline__ float siluf_(float x) { return x * __builtin_amdgcn_rcpf(1.f + __expf(-x)); }
; __device__ __forceinline__ void ssdconv_prompt_item(const bf16_t* PROJ, int row0, bool has_hist, int cgi, const float* w, const float* bias, bf16_t* XBC, float* state_out,
;                                                     const float* DT, const float* CS, bf16_t* XT1, bf16_t* XT2, bf16_t* BT) {
;     ...
;     for (int t = 0; t < 8; ++t) {
;         float cur[8];
;         unpack8(rows[t], cur);
; #pragma unroll
;         for (int e = 0; e < 8; ++e) { float v = h0[e] * wv[0][e] + h1[e] * wv[1][e] + h2[e] * wv[2][e] + cur[e] * wv[3][e] + bv[e]; o[t][e] = siluf_(v); h0[e] = h1[e]; h1[e] = h2[e]; h2[e] = cur[e]; }
;         *(u32x4*)(XBC + (size_t)(row0 + t) * XBCW + c0) = pack8(o[t]);
	v_pk_mul_f32 v[142:143], v[134:135], v[12:13] op_sel:[0,0] op_sel_hi:[1,0]
	v_pk_mul_f32 v[144:145], v[136:137], v[12:13] op_sel:[0,0] op_sel_hi:[1,0]
	v_pk_mul_f32 v[146:147], v[138:139], v[12:13] op_sel:[0,0] op_sel_hi:[1,0]
	v_exp_f32_e32 v140, v140
	v_exp_f32_e32 v141, v141
	v_exp_f32_e32 v142, v142
	v_exp_f32_e32 v143, v143
	v_exp_f32_e32 v144, v144
	v_exp_f32_e32 v145, v145
	v_exp_f32_e32 v146, v146
	v_exp_f32_e32 v147, v147
	v_pk_add_f32 v[140:141], v[140:141], v[12:13] op_sel:[0,1] op_sel_hi:[1,1]
	v_pk_add_f32 v[142:143], v[142:143], v[12:13] op_sel:[0,1] op_sel_hi:[1,1]
	v_pk_add_f32 v[144:145], v[144:145], v[12:13] op_sel:[0,1] op_sel_hi:[1,1]
	v_pk_add_f32 v[146:147], v[146:147], v[12:13] op_sel:[0,1] op_sel_hi:[1,1]
	v_rcp_f32_e32 v140, v140
	v_rcp_f32_e32 v141, v141
	v_rcp_f32_e32 v142, v142
	v_rcp_f32_e32 v143, v143
	v_rcp_f32_e32 v144, v144
	v_rcp_f32_e32 v145, v145
	v_rcp_f32_e32 v146, v146
	v_rcp_f32_e32 v147, v147
	v_pk_mul_f32 v[140:141], v[132:133], v[140:141]
	v_pk_mul_f32 v[142:143], v[134:135], v[142:143]
	v_pk_mul_f32 v[144:145], v[136:137], v[144:145]
	v_pk_mul_f32 v[146:147], v[138:139], v[146:147]
	v_cvt_pk_bf16_f32 v148, v140, v141
	v_cvt_pk_bf16_f32 v149, v142, v143
	v_cvt_pk_bf16_f32 v150, v144, v145
	v_cvt_pk_bf16_f32 v151, v146, v147
	global_store_dwordx4 v5, v[148:151], s[30:31]
	s_add_u32 s30, s30, 0x1800
	s_addc_u32 s31, s31, 0
	v_lshlrev_b32_e32 v108, 16, v76
	v_and_b32_e32 v109, 0xffff0000, v76
	v_lshlrev_b32_e32 v110, 16, v77
	v_and_b32_e32 v111, 0xffff0000, v77
	v_lshlrev_b32_e32 v112, 16, v78
	v_and_b32_e32 v113, 0xffff0000, v78
	v_lshlrev_b32_e32 v114, 16, v79
	v_and_b32_e32 v115, 0xffff0000, v79
	v_pk_mul_f32 v[132:133], v[116:117], v[16:17]
	v_pk_fma_f32 v[132:133], v[124:125], v[24:25], v[132:133]
	v_pk_fma_f32 v[132:133], v[100:101], v[32:33], v[132:133]
	v_pk_fma_f32 v[132:133], v[108:109], v[40:41], v[132:133]
	v_pk_add_f32 v[132:133], v[132:133], v[48:49]
	v_pk_mul_f32 v[134:135], v[118:119], v[18:19]
	v_pk_fma_f32 v[134:135], v[126:127], v[26:27], v[134:135]
	v_pk_fma_f32 v[134:135], v[102:103], v[34:35], v[134:135]
	v_pk_fma_f32 v[134:135], v[110:111], v[42:43], v[134:135]
	v_pk_add_f32 v[134:135], v[134:135], v[50:51]
	v_pk_mul_f32 v[136:137], v[120:121], v[20:21]
	v_pk_fma_f32 v[136:137], v[128:129], v[28:29], v[136:137]
	v_pk_fma_f32 v[136:137], v[104:105], v[36:37], v[136:137]
	v_pk_fma_f32 v[136:137], v[112:113], v[44:45], v[136:137]
	v_pk_add_f32 v[136:137], v[136:137], v[52:53]
	v_pk_mul_f32 v[138:139], v[122:123], v[22:23]
	v_pk_fma_f32 v[138:139], v[130:131], v[30:31], v[138:139]
	v_pk_fma_f32 v[138:139], v[106:107], v[38:39], v[138:139]
	v_pk_fma_f32 v[138:139], v[114:115], v[46:47], v[138:139]
	v_pk_add_f32 v[138:139], v[138:139], v[54:55]
	v_pk_mul_f32 v[140:141], v[132:133], v[12:13] op_sel:[0,0] op_sel_hi:[1,0]
	v_pk_mul_f32 v[142:143], v[134:135], v[12:13] op_sel:[0,0] op_sel_hi:[1,0]
	v_pk_mul_f32 v[144:145], v[136:137], v[12:13] op_sel:[0,0] op_sel_hi:[1,0]
	v_pk_mul_f32 v[146:147], v[138:139], v[12:13] op_sel:[0,0] op_sel_hi:[1,0]
	v_exp_f32_e32 v140, v140
	v_exp_f32_e32 v141, v141
	v_exp_f32_e32 v142, v142
	v_exp_f32_e32 v143, v143
	v_exp_f32_e32 v144, v144
	v_exp_f32_e32 v145, v145
	v_exp_f32_e32 v146, v146
	v_exp_f32_e32 v147, v147
	v_pk_add_f32 v[140:141], v[140:141], v[12:13] op_sel:[0,1] op_sel_hi:[1,1]
	v_pk_add_f32 v[142:143], v[142:143], v[12:13] op_sel:[0,1] op_sel_hi:[1,1]
	v_pk_add_f32 v[144:145], v[144:145], v[12:13] op_sel:[0,1] op_sel_hi:[1,1]
	v_pk_add_f32 v[146:147], v[146:147], v[12:13] op_sel:[0,1] op_sel_hi:[1,1]
	v_rcp_f32_e32 v140, v140
	v_rcp_f32_e32 v141, v141
	v_rcp_f32_e32 v142, v142
	v_rcp_f32_e32 v143, v143
	v_rcp_f32_e32 v144, v144
	v_rcp_f32_e32 v145, v145
	v_rcp_f32_e32 v146, v146
	v_rcp_f32_e32 v147, v147
	v_pk_mul_f32 v[140:141], v[132:133], v[140:141]
	v_pk_mul_f32 v[142:143], v[134:135], v[142:143]
	v_pk_mul_f32 v[144:145], v[136:137], v[144:145]
	v_pk_mul_f32 v[146:147], v[138:139], v[146:147]
	v_cvt_pk_bf16_f32 v148, v140, v141
	v_cvt_pk_bf16_f32 v149, v142, v143
	v_cvt_pk_bf16_f32 v150, v144, v145
	v_cvt_pk_bf16_f32 v151, v146, v147
	global_store_dwordx4 v5, v[148:151], s[30:31]
	s_add_u32 s30, s30, 0x1800
	s_addc_u32 s31, s31, 0
	v_lshlrev_b32_e32 v116, 16, v80
	v_and_b32_e32 v117, 0xffff0000, v80
	v_lshlrev_b32_e32 v118, 16, v81
	v_and_b32_e32 v119, 0xffff0000, v81
	v_lshlrev_b32_e32 v120, 16, v82
	v_and_b32_e32 v121, 0xffff0000, v82
	v_lshlrev_b32_e32 v122, 16, v83
	v_and_b32_e32 v123, 0xffff0000, v83
	v_pk_mul_f32 v[132:133], v[124:125], v[16:17]
	v_pk_fma_f32 v[132:133], v[100:101], v[24:25], v[132:133]
	v_pk_fma_f32 v[132:133], v[108:109], v[32:33], v[132:133]
	v_pk_fma_f32 v[132:133], v[116:117], v[40:41], v[132:133]
	v_pk_add_f32 v[132:133], v[132:133], v[48:49]
	v_pk_mul_f32 v[134:135], v[126:127], v[18:19]
	v_pk_fma_f32 v[134:135], v[102:103], v[26:27], v[134:135]
	v_pk_fma_f32 v[134:135], v[110:111], v[34:35], v[134:135]
	v_pk_fma_f32 v[134:135], v[118:119], v[42:43], v[134:135]
	v_pk_add_f32 v[134:135], v[134:135], v[50:51]
	v_pk_mul_f32 v[136:137], v[128:129], v[20:21]
	v_pk_fma_f32 v[136:137], v[104:105], v[28:29], v[136:137]
	v_pk_fma_f32 v[136:137], v[112:113], v[36:37], v[136:137]
	v_pk_fma_f32 v[136:137], v[120:121], v[44:45], v[136:137]
	v_pk_add_f32 v[136:137], v[136:137], v[52:53]
	v_pk_mul_f32 v[138:139], v[130:131], v[22:23]
	v_pk_fma_f32 v[138:139], v[106:107], v[30:31], v[138:139]
	v_pk_fma_f32 v[138:139], v[114:115], v[38:39], v[138:139]
	v_pk_fma_f32 v[138:139], v[122:123], v[46:47], v[138:139]
	v_pk_add_f32 v[138:139], v[138:139], v[54:55]
	v_pk_mul_f32 v[140:141], v[132:133], v[12:13] op_sel:[0,0] op_sel_hi:[1,0]
; __device__ __forceinline__ float siluf_(float x) { return x * __builtin_amdgcn_rcpf(1.f + __expf(-x)); }
; __device__ __forceinline__ void ssdconv_prompt_item(const bf16_t* PROJ, int row0, bool has_hist, int cgi, const float* w, const float* bias, bf16_t* XBC, float* state_out,
;                                                     const float* DT, const float* CS, bf16_t* XT1, bf16_t* XT2, bf16_t* BT) {
;     ...
;     for (int t = 0; t < 8; ++t) {
;         float cur[8];
;         unpack8(rows[t], cur);
; #pragma unroll
;         for (int e = 0; e < 8; ++e) { float v = h0[e] * wv[0][e] + h1[e] * wv[1][e] + h2[e] * wv[2][e] + cur[e] * wv[3][e] + bv[e]; o[t][e] = siluf_(v); h0[e] = h1[e]; h1[e] = h2[e]; h2[e] = cur[e]; }
;         *(u32x4*)(XBC + (size_t)(row0 + t) * XBCW + c0) = pack8(o[t]);
	v_pk_mul_f32 v[142:143], v[134:135], v[12:13] op_sel:[0,0] op_sel_hi:[1,0]
	v_pk_mul_f32 v[144:145], v[136:137], v[12:13] op_sel:[0,0] op_sel_hi:[1,0]
	v_pk_mul_f32 v[146:147], v[138:139], v[12:13] op_sel:[0,0] op_sel_hi:[1,0]
	v_exp_f32_e32 v140, v140
	v_exp_f32_e32 v141, v141
	v_exp_f32_e32 v142, v142
	v_exp_f32_e32 v143, v143
	v_exp_f32_e32 v144, v144
	v_exp_f32_e32 v145, v145
	v_exp_f32_e32 v146, v146
	v_exp_f32_e32 v147, v147
	v_pk_add_f32 v[140:141], v[140:141], v[12:13] op_sel:[0,1] op_sel_hi:[1,1]
	v_pk_add_f32 v[142:143], v[142:143], v[12:13] op_sel:[0,1] op_sel_hi:[1,1]
	v_pk_add_f32 v[144:145], v[144:145], v[12:13] op_sel:[0,1] op_sel_hi:[1,1]
	v_pk_add_f32 v[146:147], v[146:147], v[12:13] op_sel:[0,1] op_sel_hi:[1,1]
	v_rcp_f32_e32 v140, v140
	v_rcp_f32_e32 v141, v141
	v_rcp_f32_e32 v142, v142
	v_rcp_f32_e32 v143, v143
	v_rcp_f32_e32 v144, v144
	v_rcp_f32_e32 v145, v145
	v_rcp_f32_e32 v146, v146
	v_rcp_f32_e32 v147, v147
	v_pk_mul_f32 v[140:141], v[132:133], v[140:141]
	v_pk_mul_f32 v[142:143], v[134:135], v[142:143]
	v_pk_mul_f32 v[144:145], v[136:137], v[144:145]
	v_pk_mul_f32 v[146:147], v[138:139], v[146:147]
	v_cvt_pk_bf16_f32 v148, v140, v141
	v_cvt_pk_bf16_f32 v149, v142, v143
	v_cvt_pk_bf16_f32 v150, v144, v145
	v_cvt_pk_bf16_f32 v151, v146, v147
	global_store_dwordx4 v5, v[148:151], s[30:31]
	s_add_u32 s30, s30, 0x1800
	s_addc_u32 s31, s31, 0
	v_lshlrev_b32_e32 v124, 16, v84
	v_and_b32_e32 v125, 0xffff0000, v84
	v_lshlrev_b32_e32 v126, 16, v85
	v_and_b32_e32 v127, 0xffff0000, v85
	v_lshlrev_b32_e32 v128, 16, v86
	v_and_b32_e32 v129, 0xffff0000, v86
	v_lshlrev_b32_e32 v130, 16, v87
	v_and_b32_e32 v131, 0xffff0000, v87
	v_pk_mul_f32 v[132:133], v[100:101], v[16:17]
	v_pk_fma_f32 v[132:133], v[108:109], v[24:25], v[132:133]
	v_pk_fma_f32 v[132:133], v[116:117], v[32:33], v[132:133]
	v_pk_fma_f32 v[132:133], v[124:125], v[40:41], v[132:133]
	v_pk_add_f32 v[132:133], v[132:133], v[48:49]
	v_pk_mul_f32 v[134:135], v[102:103], v[18:19]
	v_pk_fma_f32 v[134:135], v[110:111], v[26:27], v[134:135]
	v_pk_fma_f32 v[134:135], v[118:119], v[34:35], v[134:135]
	v_pk_fma_f32 v[134:135], v[126:127], v[42:43], v[134:135]
	v_pk_add_f32 v[134:135], v[134:135], v[50:51]
	v_pk_mul_f32 v[136:137], v[104:105], v[20:21]
	v_pk_fma_f32 v[136:137], v[112:113], v[28:29], v[136:137]
	v_pk_fma_f32 v[136:137], v[120:121], v[36:37], v[136:137]
	v_pk_fma_f32 v[136:137], v[128:129], v[44:45], v[136:137]
	v_pk_add_f32 v[136:137], v[136:137], v[52:53]
	v_pk_mul_f32 v[138:139], v[106:107], v[22:23]
	v_pk_fma_f32 v[138:139], v[114:115], v[30:31], v[138:139]
	v_pk_fma_f32 v[138:139], v[122:123], v[38:39], v[138:139]
	v_pk_fma_f32 v[138:139], v[130:131], v[46:47], v[138:139]
	v_pk_add_f32 v[138:139], v[138:139], v[54:55]
	v_pk_mul_f32 v[140:141], v[132:133], v[12:13] op_sel:[0,0] op_sel_hi:[1,0]
	v_pk_mul_f32 v[142:143], v[134:135], v[12:13] op_sel:[0,0] op_sel_hi:[1,0]
	v_pk_mul_f32 v[144:145], v[136:137], v[12:13] op_sel:[0,0] op_sel_hi:[1,0]
	v_pk_mul_f32 v[146:147], v[138:139], v[12:13] op_sel:[0,0] op_sel_hi:[1,0]
	v_exp_f32_e32 v140, v140
	v_exp_f32_e32 v141, v141
	v_exp_f32_e32 v142, v142
	v_exp_f32_e32 v143, v143
	v_exp_f32_e32 v144, v144
	v_exp_f32_e32 v145, v145
	v_exp_f32_e32 v146, v146
	v_exp_f32_e32 v147, v147
	v_pk_add_f32 v[140:141], v[140:141], v[12:13] op_sel:[0,1] op_sel_hi:[1,1]
	v_pk_add_f32 v[142:143], v[142:143], v[12:13] op_sel:[0,1] op_sel_hi:[1,1]
	v_pk_add_f32 v[144:145], v[144:145], v[12:13] op_sel:[0,1] op_sel_hi:[1,1]
	v_pk_add_f32 v[146:147], v[146:147], v[12:13] op_sel:[0,1] op_sel_hi:[1,1]
	v_rcp_f32_e32 v140, v140
	v_rcp_f32_e32 v141, v141
	v_rcp_f32_e32 v142, v142
	v_rcp_f32_e32 v143, v143
	v_rcp_f32_e32 v144, v144
	v_rcp_f32_e32 v145, v145
	v_rcp_f32_e32 v146, v146
	v_rcp_f32_e32 v147, v147
	v_pk_mul_f32 v[140:141], v[132:133], v[140:141]
	v_pk_mul_f32 v[142:143], v[134:135], v[142:143]
	v_pk_mul_f32 v[144:145], v[136:137], v[144:145]
	v_pk_mul_f32 v[146:147], v[138:139], v[146:147]
	v_cvt_pk_bf16_f32 v148, v140, v141
	v_cvt_pk_bf16_f32 v149, v142, v143
	v_cvt_pk_bf16_f32 v150, v144, v145
	v_cvt_pk_bf16_f32 v151, v146, v147
	global_store_dwordx4 v5, v[148:151], s[30:31]
	s_add_u32 s30, s30, 0x1800
	s_addc_u32 s31, s31, 0
	v_lshlrev_b32_e32 v100, 16, v88
	v_and_b32_e32 v101, 0xffff0000, v88
	v_lshlrev_b32_e32 v102, 16, v89
	v_and_b32_e32 v103, 0xffff0000, v89
	v_lshlrev_b32_e32 v104, 16, v90
	v_and_b32_e32 v105, 0xffff0000, v90
	v_lshlrev_b32_e32 v106, 16, v91
	v_and_b32_e32 v107, 0xffff0000, v91
	v_pk_mul_f32 v[132:133], v[108:109], v[16:17]
	v_pk_fma_f32 v[132:133], v[116:117], v[24:25], v[132:133]
	v_pk_fma_f32 v[132:133], v[124:125], v[32:33], v[132:133]
	v_pk_fma_f32 v[132:133], v[100:101], v[40:41], v[132:133]
	v_pk_add_f32 v[132:133], v[132:133], v[48:49]
	v_pk_mul_f32 v[134:135], v[110:111], v[18:19]
	v_pk_fma_f32 v[134:135], v[118:119], v[26:27], v[134:135]
	v_pk_fma_f32 v[134:135], v[126:127], v[34:35], v[134:135]
	v_pk_fma_f32 v[134:135], v[102:103], v[42:43], v[134:135]
	v_pk_add_f32 v[134:135], v[134:135], v[50:51]
	v_pk_mul_f32 v[136:137], v[112:113], v[20:21]
	v_pk_fma_f32 v[136:137], v[120:121], v[28:29], v[136:137]
	v_pk_fma_f32 v[136:137], v[128:129], v[36:37], v[136:137]
	v_pk_fma_f32 v[136:137], v[104:105], v[44:45], v[136:137]
	v_pk_add_f32 v[136:137], v[136:137], v[52:53]
	v_pk_mul_f32 v[138:139], v[114:115], v[22:23]
	v_pk_fma_f32 v[138:139], v[122:123], v[30:31], v[138:139]
	v_pk_fma_f32 v[138:139], v[130:131], v[38:39], v[138:139]
	v_pk_fma_f32 v[138:139], v[106:107], v[46:47], v[138:139]
	v_pk_add_f32 v[138:139], v[138:139], v[54:55]
	v_pk_mul_f32 v[140:141], v[132:133], v[12:13] op_sel:[0,0] op_sel_hi:[1,0]
; __device__ __forceinline__ float siluf_(float x) { return x * __builtin_amdgcn_rcpf(1.f + __expf(-x)); }
; __device__ __forceinline__ void ssdconv_prompt_item(const bf16_t* PROJ, int row0, bool has_hist, int cgi, const float* w, const float* bias, bf16_t* XBC, float* state_out,
;                                                     const float* DT, const float* CS, bf16_t* XT1, bf16_t* XT2, bf16_t* BT) {
;     ...
;     for (int t = 0; t < 8; ++t) {
;         float cur[8];
;         unpack8(rows[t], cur);
; #pragma unroll
;         for (int e = 0; e < 8; ++e) { float v = h0[e] * wv[0][e] + h1[e] * wv[1][e] + h2[e] * wv[2][e] + cur[e] * wv[3][e] + bv[e]; o[t][e] = siluf_(v); h0[e] = h1[e]; h1[e] = h2[e]; h2[e] = cur[e]; }
;         *(u32x4*)(XBC + (size_t)(row0 + t) * XBCW + c0) = pack8(o[t]);
	v_pk_mul_f32 v[142:143], v[134:135], v[12:13] op_sel:[0,0] op_sel_hi:[1,0]
	v_pk_mul_f32 v[144:145], v[136:137], v[12:13] op_sel:[0,0] op_sel_hi:[1,0]
	v_pk_mul_f32 v[146:147], v[138:139], v[12:13] op_sel:[0,0] op_sel_hi:[1,0]
	v_exp_f32_e32 v140, v140
	v_exp_f32_e32 v141, v141
	v_exp_f32_e32 v142, v142
	v_exp_f32_e32 v143, v143
	v_exp_f32_e32 v144, v144
	v_exp_f32_e32 v145, v145
	v_exp_f32_e32 v146, v146
	v_exp_f32_e32 v147, v147
	v_pk_add_f32 v[140:141], v[140:141], v[12:13] op_sel:[0,1] op_sel_hi:[1,1]
	v_pk_add_f32 v[142:143], v[142:143], v[12:13] op_sel:[0,1] op_sel_hi:[1,1]
	v_pk_add_f32 v[144:145], v[144:145], v[12:13] op_sel:[0,1] op_sel_hi:[1,1]
	v_pk_add_f32 v[146:147], v[146:147], v[12:13] op_sel:[0,1] op_sel_hi:[1,1]
	v_rcp_f32_e32 v140, v140
	v_rcp_f32_e32 v141, v141
	v_rcp_f32_e32 v142, v142
	v_rcp_f32_e32 v143, v143
	v_rcp_f32_e32 v144, v144
	v_rcp_f32_e32 v145, v145
	v_rcp_f32_e32 v146, v146
	v_rcp_f32_e32 v147, v147
	v_pk_mul_f32 v[140:141], v[132:133], v[140:141]
	v_pk_mul_f32 v[142:143], v[134:135], v[142:143]
	v_pk_mul_f32 v[144:145], v[136:137], v[144:145]
	v_pk_mul_f32 v[146:147], v[138:139], v[146:147]
	v_cvt_pk_bf16_f32 v148, v140, v141
	v_cvt_pk_bf16_f32 v149, v142, v143
	v_cvt_pk_bf16_f32 v150, v144, v145
	v_cvt_pk_bf16_f32 v151, v146, v147
	global_store_dwordx4 v5, v[148:151], s[30:31]
	s_add_u32 s30, s30, 0x1800
	s_addc_u32 s31, s31, 0
	v_lshlrev_b32_e32 v108, 16, v92
	v_and_b32_e32 v109, 0xffff0000, v92
	v_lshlrev_b32_e32 v110, 16, v93
	v_and_b32_e32 v111, 0xffff0000, v93
	v_lshlrev_b32_e32 v112, 16, v94
	v_and_b32_e32 v113, 0xffff0000, v94
	v_lshlrev_b32_e32 v114, 16, v95
	v_and_b32_e32 v115, 0xffff0000, v95
	v_pk_mul_f32 v[132:133], v[116:117], v[16:17]
	v_pk_fma_f32 v[132:133], v[124:125], v[24:25], v[132:133]
	v_pk_fma_f32 v[132:133], v[100:101], v[32:33], v[132:133]
	v_pk_fma_f32 v[132:133], v[108:109], v[40:41], v[132:133]
	v_pk_add_f32 v[132:133], v[132:133], v[48:49]
	v_pk_mul_f32 v[134:135], v[118:119], v[18:19]
	v_pk_fma_f32 v[134:135], v[126:127], v[26:27], v[134:135]
	v_pk_fma_f32 v[134:135], v[102:103], v[34:35], v[134:135]
	v_pk_fma_f32 v[134:135], v[110:111], v[42:43], v[134:135]
	v_pk_add_f32 v[134:135], v[134:135], v[50:51]
	v_pk_mul_f32 v[136:137], v[120:121], v[20:21]
	v_pk_fma_f32 v[136:137], v[128:129], v[28:29], v[136:137]
	v_pk_fma_f32 v[136:137], v[104:105], v[36:37], v[136:137]
	v_pk_fma_f32 v[136:137], v[112:113], v[44:45], v[136:137]
	v_pk_add_f32 v[136:137], v[136:137], v[52:53]
	v_pk_mul_f32 v[138:139], v[122:123], v[22:23]
	v_pk_fma_f32 v[138:139], v[130:131], v[30:31], v[138:139]
	v_pk_fma_f32 v[138:139], v[106:107], v[38:39], v[138:139]
	v_pk_fma_f32 v[138:139], v[114:115], v[46:47], v[138:139]
	v_pk_add_f32 v[138:139], v[138:139], v[54:55]
	v_pk_mul_f32 v[140:141], v[132:133], v[12:13] op_sel:[0,0] op_sel_hi:[1,0]
	v_pk_mul_f32 v[142:143], v[134:135], v[12:13] op_sel:[0,0] op_sel_hi:[1,0]
	v_pk_mul_f32 v[144:145], v[136:137], v[12:13] op_sel:[0,0] op_sel_hi:[1,0]
	v_pk_mul_f32 v[146:147], v[138:139], v[12:13] op_sel:[0,0] op_sel_hi:[1,0]
	v_exp_f32_e32 v140, v140
	v_exp_f32_e32 v141, v141
	v_exp_f32_e32 v142, v142
	v_exp_f32_e32 v143, v143
	v_exp_f32_e32 v144, v144
	v_exp_f32_e32 v145, v145
	v_exp_f32_e32 v146, v146
	v_exp_f32_e32 v147, v147
	v_pk_add_f32 v[140:141], v[140:141], v[12:13] op_sel:[0,1] op_sel_hi:[1,1]
	v_pk_add_f32 v[142:143], v[142:143], v[12:13] op_sel:[0,1] op_sel_hi:[1,1]
	v_pk_add_f32 v[144:145], v[144:145], v[12:13] op_sel:[0,1] op_sel_hi:[1,1]
	v_pk_add_f32 v[146:147], v[146:147], v[12:13] op_sel:[0,1] op_sel_hi:[1,1]
	v_rcp_f32_e32 v140, v140
	v_rcp_f32_e32 v141, v141
	v_rcp_f32_e32 v142, v142
	v_rcp_f32_e32 v143, v143
	v_rcp_f32_e32 v144, v144
	v_rcp_f32_e32 v145, v145
	v_rcp_f32_e32 v146, v146
	v_rcp_f32_e32 v147, v147
	v_pk_mul_f32 v[140:141], v[132:133], v[140:141]
; __device__ __forceinline__ float siluf_(float x) { return x * __builtin_amdgcn_rcpf(1.f + __expf(-x)); }
; __device__ __forceinline__ void ssdconv_prompt_item(const bf16_t* PROJ, int row0, bool has_hist, int cgi, const float* w, const float* bias, bf16_t* XBC, float* state_out,
;                                                     const float* DT, const float* CS, bf16_t* XT1, bf16_t* XT2, bf16_t* BT) {
;     ...
;     for (int t = 0; t < 8; ++t) {
;         float cur[8];
;         unpack8(rows[t], cur);
; #pragma unroll
;         for (int e = 0; e < 8; ++e) { float v = h0[e] * wv[0][e] + h1[e] * wv[1][e] + h2[e] * wv[2][e] + cur[e] * wv[3][e] + bv[e]; o[t][e] = siluf_(v); h0[e] = h1[e]; h1[e] = h2[e]; h2[e] = cur[e]; }
;         *(u32x4*)(XBC + (size_t)(row0 + t) * XBCW + c0) = pack8(o[t]);
;     }
;     if (state_out) {
;         *(f32x4*)(state_out + 0 * XBCW + c0) = (f32x4){h0[0], h0[1], h0[2], h0[3]}; *(f32x4*)(state_out + 0 * XBCW + c0 + 4) = (f32x4){h0[4], h0[5], h0[6], h0[7]};
;         *(f32x4*)(state_out + 1 * XBCW + c0) = (f32x4){h1[0], h1[1], h1[2], h1[3]}; *(f32x4*)(state_out + 1 * XBCW + c0 + 4) = (f32x4){h1[4], h1[5], h1[6], h1[7]};
;         *(f32x4*)(state_out + 2 * XBCW + c0) = (f32x4){h2[0], h2[1], h2[2], h2[3]}; *(f32x4*)(state_out + 2 * XBCW + c0 + 4) = (f32x4){h2[4], h2[5], h2[6], h2[7]};
	v_pk_mul_f32 v[142:143], v[134:135], v[142:143]
	v_pk_mul_f32 v[144:145], v[136:137], v[144:145]
	v_pk_mul_f32 v[146:147], v[138:139], v[146:147]
	v_cvt_pk_bf16_f32 v148, v140, v141
	v_cvt_pk_bf16_f32 v149, v142, v143
	v_cvt_pk_bf16_f32 v150, v144, v145
	v_cvt_pk_bf16_f32 v151, v146, v147
	global_store_dwordx4 v5, v[148:151], s[30:31]
	s_add_u32 s30, s30, 0x1800
	s_addc_u32 s31, s31, 0
	v_lshlrev_b32_e32 v116, 16, v96
	v_and_b32_e32 v117, 0xffff0000, v96
	v_lshlrev_b32_e32 v118, 16, v97
	v_and_b32_e32 v119, 0xffff0000, v97
	v_lshlrev_b32_e32 v120, 16, v98
	v_and_b32_e32 v121, 0xffff0000, v98
	v_lshlrev_b32_e32 v122, 16, v99
	v_and_b32_e32 v123, 0xffff0000, v99
	v_pk_mul_f32 v[132:133], v[124:125], v[16:17]
	v_pk_fma_f32 v[132:133], v[100:101], v[24:25], v[132:133]
	v_pk_fma_f32 v[132:133], v[108:109], v[32:33], v[132:133]
	v_pk_fma_f32 v[132:133], v[116:117], v[40:41], v[132:133]
	v_pk_add_f32 v[132:133], v[132:133], v[48:49]
	v_pk_mul_f32 v[134:135], v[126:127], v[18:19]
	v_pk_fma_f32 v[134:135], v[102:103], v[26:27], v[134:135]
	v_pk_fma_f32 v[134:135], v[110:111], v[34:35], v[134:135]
	v_pk_fma_f32 v[134:135], v[118:119], v[42:43], v[134:135]
	v_pk_add_f32 v[134:135], v[134:135], v[50:51]
	v_pk_mul_f32 v[136:137], v[128:129], v[20:21]
	v_pk_fma_f32 v[136:137], v[104:105], v[28:29], v[136:137]
	v_pk_fma_f32 v[136:137], v[112:113], v[36:37], v[136:137]
	v_pk_fma_f32 v[136:137], v[120:121], v[44:45], v[136:137]
	v_pk_add_f32 v[136:137], v[136:137], v[52:53]
	v_pk_mul_f32 v[138:139], v[130:131], v[22:23]
	v_pk_fma_f32 v[138:139], v[106:107], v[30:31], v[138:139]
	v_pk_fma_f32 v[138:139], v[114:115], v[38:39], v[138:139]
	v_pk_fma_f32 v[138:139], v[122:123], v[46:47], v[138:139]
	v_pk_add_f32 v[138:139], v[138:139], v[54:55]
	v_pk_mul_f32 v[140:141], v[132:133], v[12:13] op_sel:[0,0] op_sel_hi:[1,0]
	v_pk_mul_f32 v[142:143], v[134:135], v[12:13] op_sel:[0,0] op_sel_hi:[1,0]
	v_pk_mul_f32 v[144:145], v[136:137], v[12:13] op_sel:[0,0] op_sel_hi:[1,0]
	v_pk_mul_f32 v[146:147], v[138:139], v[12:13] op_sel:[0,0] op_sel_hi:[1,0]
	v_exp_f32_e32 v140, v140
	v_exp_f32_e32 v141, v141
	v_exp_f32_e32 v142, v142
	v_exp_f32_e32 v143, v143
	v_exp_f32_e32 v144, v144
	v_exp_f32_e32 v145, v145
	v_exp_f32_e32 v146, v146
	v_exp_f32_e32 v147, v147
	v_pk_add_f32 v[140:141], v[140:141], v[12:13] op_sel:[0,1] op_sel_hi:[1,1]
	v_pk_add_f32 v[142:143], v[142:143], v[12:13] op_sel:[0,1] op_sel_hi:[1,1]
	v_pk_add_f32 v[144:145], v[144:145], v[12:13] op_sel:[0,1] op_sel_hi:[1,1]
	v_pk_add_f32 v[146:147], v[146:147], v[12:13] op_sel:[0,1] op_sel_hi:[1,1]
	v_rcp_f32_e32 v140, v140
	v_rcp_f32_e32 v141, v141
	v_rcp_f32_e32 v142, v142
	v_rcp_f32_e32 v143, v143
	v_rcp_f32_e32 v144, v144
	v_rcp_f32_e32 v145, v145
	v_rcp_f32_e32 v146, v146
	v_rcp_f32_e32 v147, v147
	v_pk_mul_f32 v[140:141], v[132:133], v[140:141]
	v_pk_mul_f32 v[142:143], v[134:135], v[142:143]
	v_pk_mul_f32 v[144:145], v[136:137], v[144:145]
	v_pk_mul_f32 v[146:147], v[138:139], v[146:147]
	v_cvt_pk_bf16_f32 v148, v140, v141
	v_cvt_pk_bf16_f32 v149, v142, v143
	v_cvt_pk_bf16_f32 v150, v144, v145
	v_cvt_pk_bf16_f32 v151, v146, v147
	global_store_dwordx4 v5, v[148:151], s[30:31]
	s_and_b32 s33, s5, 31
	s_cmp_eq_u32 s33, 31
	s_cbranch_scc0 .Lp2b_nostate_c
	s_mov_b64 s[48:49], exec
	s_and_b64 exec, exec, s[46:47]
	global_store_dwordx4 v11, v[100:103], s[38:39]
	global_store_dwordx4 v11, v[104:107], s[38:39] offset:16
	s_add_u32 s38, s38, 0x3000
	s_addc_u32 s39, s39, 0
	global_store_dwordx4 v11, v[108:111], s[38:39]
	global_store_dwordx4 v11, v[112:115], s[38:39] offset:16
	s_add_u32 s38, s38, 0x3000
	s_addc_u32 s39, s39, 0
	global_store_dwordx4 v11, v[116:119], s[38:39]
	global_store_dwordx4 v11, v[120:123], s[38:39] offset:16
	s_mov_b64 exec, s[48:49]
.Lp2b_nostate_c:
.Lp2b_next:
	s_add_u32 s7, s7, 1
	s_cmp_lt_u32 s7, 3
	s_cbranch_scc1 .Lp2b_item
